# baseline (speedup 1.0000x reference)
; #define PG8_STAGE(bufoff, gbase, voff) do { _Pragma("unroll") for (int _i = 0; _i < 2; ++_i) \
;         __builtin_amdgcn_global_load_lds((const unsigned*)((const char*)(gbase) + (voff)[_i]), (PG8_LAS unsigned*)(lds + (bufoff) + ldsw + _i * 8192), 16, 0, 0); } while (0)
; #define PG8_LDA(dst, b, h) do { _Pragma("unroll") for (int m = 0; m < 4; ++m) _Pragma("unroll") for (int k = 0; k < 2; ++k) dst[m][k] = *(const PG8_LAS bf16x8*)(lds + PG8_SA(b, h) + aoff + m * 2048 + k * 1024); } while (0)
; #define PG8_LDB(dst, b, h) do { _Pragma("unroll") for (int n = 0; n < 2; ++n) _Pragma("unroll") for (int k = 0; k < 2; ++k) dst[n][k] = *(const PG8_LAS bf16x8*)(lds + PG8_SB(b, h) + boff + n * 2048 + k * 1024); } while (0)
; #define PG8_MMA(ai, bj, At, Bt) do { __builtin_amdgcn_s_setprio(1); _Pragma("unroll") for (int m = 0; m < 4; ++m) _Pragma("unroll") for (int n = 0; n < 2; ++n) _Pragma("unroll") for (int k = 0; k < 2; ++k) \
;         acc[ai][bj][m][n] = __builtin_amdgcn_mfma_f32_16x16x32_bf16(Bt[n][k], At[m][k], acc[ai][bj][m][n], 0, 0, 0); __builtin_amdgcn_s_setprio(0); } while (0)
; #define PG8_WAIT_V(n) asm volatile("s_waitcnt vmcnt(" #n ")" ::: "memory")
; #define PG8_WAIT_L(n) asm volatile("s_waitcnt lgkmcnt(" #n ")" ::: "memory")
; #define PG8_BAR __builtin_amdgcn_s_barrier()
; #define PG8_SCHED __builtin_amdgcn_sched_barrier(0)
; template <class Epi, class Sched, bool ALIGN_EPI = false, bool SP2 = false>
; __device__ __forceinline__ void gemm_phase(PG8_LAS unsigned char* lds, const Gemm g, const Sched& S, const Epi& E, int wv) {
;     ...
;             const bool last = (t == nt - 2);
;             const char* a1 = cA + (size_t)(t + 1) * kstep;
;             const char* a2 = last ? nA : cA + (size_t)(t + 2) * kstep; const char* b2 = last ? nB : cB + (size_t)(t + 2) * kstep;
;             const char* a3 = a2 + kstep; const char* b3 = b2 + kstep;
;             if (last && has_next) S.a_ready(nxt);
;             if constexpr (SP2) {
;             PG8_LDB(B0, 0, 0); PG8_LDB(B1, 0, 1); PG8_SCHED; PG8_LDA(At, 0, 0); PG8_STAGE(PG8_SA(1, 1), a1 + hstepA, voffA);
;             PG8_WAIT_V(8); PG8_WAIT_L(0); PG8_BAR; PG8_MMA(0, 0, At, B0); PG8_MMA(0, 1, At, B1); PG8_BAR; PG8_SCHED;
;             PG8_LDA(At, 0, 1); PG8_STAGE(PG8_SB(0, 0), b2, voffB); PG8_STAGE(PG8_SB(0, 1), b2 + hstepB, voffB); PG8_STAGE(PG8_SA(0, 0), a2, voffA);
.LBB0_59:
	s_add_u32 s0, s12, 0x100
	s_addc_u32 s1, s13, 0
	s_add_i32 s96, 0, 0x10000
	s_cmp_eq_u32 s79, 60
	s_cselect_b32 s17, s9, s1
	s_cselect_b32 s16, s8, s0
	v_add_u32_e32 v142, s96, v145
	s_cselect_b32 s15, s7, s77
	s_cselect_b32 s14, s75, s76
	s_add_i32 s97, 0, 0x14000
	ds_read_b128 v[158:161], v142
	ds_read_b128 v[162:165], v142 offset:1024
	ds_read_b128 v[166:169], v142 offset:2048
	ds_read_b128 v[170:173], v142 offset:3072
	v_add_u32_e32 v142, s97, v145
	ds_read_b128 v[174:177], v142
	ds_read_b128 v[178:181], v142 offset:1024
	ds_read_b128 v[182:185], v142 offset:2048
	ds_read_b128 v[186:189], v142 offset:3072
	v_lshl_add_u64 v[142:143], s[12:13], 0, v[138:139]
	s_add_i32 m0, s31, 0xc000
	ds_read_b128 v[190:193], v153
	ds_read_b128 v[198:201], v153 offset:1024
	ds_read_b128 v[218:221], v153 offset:2048
	ds_read_b128 v[222:225], v153 offset:3072
	ds_read_b128 v[226:229], v153 offset:4096
	ds_read_b128 v[230:233], v153 offset:5120
	ds_read_b128 v[234:237], v153 offset:6144
	ds_read_b128 v[238:241], v153 offset:7168
	global_load_lds_dwordx4 v[142:143], off
	v_lshl_add_u64 v[142:143], s[12:13], 0, v[140:141]
	s_add_i32 m0, s31, 0xe000
	s_nop 0
	global_load_lds_dwordx4 v[142:143], off
	s_waitcnt vmcnt(8) lgkmcnt(0)
	s_barrier
	s_setprio 1
	v_mfma_f32_16x16x32_bf16 v[126:129], v[158:161], v[190:193], v[126:129]
	v_mfma_f32_16x16x32_bf16 v[122:125], v[166:169], v[190:193], v[122:125]
	v_mfma_f32_16x16x32_bf16 v[118:121], v[158:161], v[218:221], v[118:121]
	v_mfma_f32_16x16x32_bf16 v[110:113], v[166:169], v[218:221], v[110:113]
	v_mfma_f32_16x16x32_bf16 v[102:105], v[158:161], v[226:229], v[102:105]
	v_mfma_f32_16x16x32_bf16 v[94:97], v[166:169], v[226:229], v[94:97]
	v_mfma_f32_16x16x32_bf16 v[86:89], v[158:161], v[234:237], v[86:89]
	v_mfma_f32_16x16x32_bf16 v[78:81], v[166:169], v[234:237], v[78:81]
	v_mfma_f32_16x16x32_bf16 v[126:129], v[162:165], v[198:201], v[126:129]
	v_mfma_f32_16x16x32_bf16 v[122:125], v[170:173], v[198:201], v[122:125]
	v_mfma_f32_16x16x32_bf16 v[118:121], v[162:165], v[222:225], v[118:121]
	v_mfma_f32_16x16x32_bf16 v[110:113], v[170:173], v[222:225], v[110:113]
	v_mfma_f32_16x16x32_bf16 v[102:105], v[162:165], v[230:233], v[102:105]
	v_mfma_f32_16x16x32_bf16 v[94:97], v[170:173], v[230:233], v[94:97]
	v_mfma_f32_16x16x32_bf16 v[86:89], v[162:165], v[238:241], v[86:89]
	v_mfma_f32_16x16x32_bf16 v[78:81], v[170:173], v[238:241], v[78:81]
	v_mfma_f32_16x16x32_bf16 v[114:117], v[174:177], v[190:193], v[114:117]
	v_mfma_f32_16x16x32_bf16 v[106:109], v[182:185], v[190:193], v[106:109]
	v_mfma_f32_16x16x32_bf16 v[98:101], v[174:177], v[218:221], v[98:101]
	v_mfma_f32_16x16x32_bf16 v[90:93], v[182:185], v[218:221], v[90:93]
	v_mfma_f32_16x16x32_bf16 v[82:85], v[174:177], v[226:229], v[82:85]
	v_mfma_f32_16x16x32_bf16 v[74:77], v[182:185], v[226:229], v[74:77]
	v_mfma_f32_16x16x32_bf16 v[70:73], v[174:177], v[234:237], v[70:73]
	v_mfma_f32_16x16x32_bf16 v[66:69], v[182:185], v[234:237], v[66:69]
	v_mfma_f32_16x16x32_bf16 v[114:117], v[178:181], v[198:201], v[114:117]
	v_mfma_f32_16x16x32_bf16 v[106:109], v[186:189], v[198:201], v[106:109]
	v_mfma_f32_16x16x32_bf16 v[98:101], v[178:181], v[222:225], v[98:101]
	v_mfma_f32_16x16x32_bf16 v[90:93], v[186:189], v[222:225], v[90:93]
	v_mfma_f32_16x16x32_bf16 v[82:85], v[178:181], v[230:233], v[82:85]
	v_mfma_f32_16x16x32_bf16 v[74:77], v[186:189], v[230:233], v[74:77]
	v_mfma_f32_16x16x32_bf16 v[70:73], v[178:181], v[238:241], v[70:73]
	v_mfma_f32_16x16x32_bf16 v[66:69], v[186:189], v[238:241], v[66:69]
	s_setprio 0
	s_barrier
	s_add_i32 s12, s96, s30
	v_lshl_add_u64 v[142:143], s[14:15], 0, v[132:133]
	s_mov_b32 m0, s12
	ds_read_b128 v[190:193], v153 offset:16384
	ds_read_b128 v[198:201], v153 offset:17408
	ds_read_b128 v[218:221], v153 offset:18432
	ds_read_b128 v[222:225], v153 offset:19456
	ds_read_b128 v[226:229], v153 offset:20480
	ds_read_b128 v[230:233], v153 offset:21504
	ds_read_b128 v[234:237], v153 offset:22528
	ds_read_b128 v[238:241], v153 offset:23552
	global_load_lds_dwordx4 v[142:143], off
	s_add_i32 m0, s12, 0x2000
	s_add_u32 s12, s14, 0x100000
	v_lshl_add_u64 v[154:155], s[14:15], 0, v[136:137]
	s_addc_u32 s13, s15, 0
	s_add_i32 s96, s97, s30
	global_load_lds_dwordx4 v[154:155], off
	v_lshl_add_u64 v[194:195], s[12:13], 0, v[132:133]
	s_mov_b32 m0, s96
	v_lshl_add_u64 v[196:197], s[16:17], 0, v[134:135]
	global_load_lds_dwordx4 v[194:195], off
	v_lshl_add_u64 v[194:195], s[12:13], 0, v[136:137]
	s_add_i32 m0, s96, 0x2000
	s_nop 0
	global_load_lds_dwordx4 v[194:195], off
	v_lshl_add_u64 v[194:195], s[16:17], 0, v[130:131]
	s_mov_b32 m0, s31
	s_nop 0
	global_load_lds_dwordx4 v[194:195], off
	s_mov_b32 m0, s33
	s_nop 0
	global_load_lds_dwordx4 v[196:197], off
	s_waitcnt vmcnt(8) lgkmcnt(0)
	s_barrier
; #define PG8_STAGE(bufoff, gbase, voff) do { _Pragma("unroll") for (int _i = 0; _i < 2; ++_i) \
;         __builtin_amdgcn_global_load_lds((const unsigned*)((const char*)(gbase) + (voff)[_i]), (PG8_LAS unsigned*)(lds + (bufoff) + ldsw + _i * 8192), 16, 0, 0); } while (0)
; #define PG8_LDA(dst, b, h) do { _Pragma("unroll") for (int m = 0; m < 4; ++m) _Pragma("unroll") for (int k = 0; k < 2; ++k) dst[m][k] = *(const PG8_LAS bf16x8*)(lds + PG8_SA(b, h) + aoff + m * 2048 + k * 1024); } while (0)
; #define PG8_LDB(dst, b, h) do { _Pragma("unroll") for (int n = 0; n < 2; ++n) _Pragma("unroll") for (int k = 0; k < 2; ++k) dst[n][k] = *(const PG8_LAS bf16x8*)(lds + PG8_SB(b, h) + boff + n * 2048 + k * 1024); } while (0)
; #define PG8_MMA(ai, bj, At, Bt) do { __builtin_amdgcn_s_setprio(1); _Pragma("unroll") for (int m = 0; m < 4; ++m) _Pragma("unroll") for (int n = 0; n < 2; ++n) _Pragma("unroll") for (int k = 0; k < 2; ++k) \
;         acc[ai][bj][m][n] = __builtin_amdgcn_mfma_f32_16x16x32_bf16(Bt[n][k], At[m][k], acc[ai][bj][m][n], 0, 0, 0); __builtin_amdgcn_s_setprio(0); } while (0)
; #define PG8_WAIT_V(n) asm volatile("s_waitcnt vmcnt(" #n ")" ::: "memory")
; #define PG8_WAIT_L(n) asm volatile("s_waitcnt lgkmcnt(" #n ")" ::: "memory")
; #define PG8_BAR __builtin_amdgcn_s_barrier()
; #define PG8_SCHED __builtin_amdgcn_sched_barrier(0)
; template <class Epi, class Sched, bool ALIGN_EPI = false, bool SP2 = false>
; __device__ __forceinline__ void gemm_phase(PG8_LAS unsigned char* lds, const Gemm g, const Sched& S, const Epi& E, int wv) {
;     ...
;             PG8_WAIT_V(8); PG8_WAIT_L(0); PG8_BAR; PG8_MMA(1, 0, At, B0); PG8_MMA(1, 1, At, B1); PG8_BAR; PG8_SCHED;
;             PG8_LDB(B0, 1, 0); PG8_LDB(B1, 1, 1); PG8_SCHED; PG8_LDA(At, 1, 0); PG8_STAGE(PG8_SA(0, 1), a2 + hstepA, voffA);
;             PG8_WAIT_V(8); PG8_WAIT_L(0); PG8_BAR; PG8_MMA(0, 0, At, B0); PG8_MMA(0, 1, At, B1); PG8_BAR; PG8_SCHED;
	s_setprio 1
	v_mfma_f32_16x16x32_bf16 v[62:65], v[158:161], v[190:193], v[62:65]
	v_mfma_f32_16x16x32_bf16 v[58:61], v[166:169], v[190:193], v[58:61]
	v_mfma_f32_16x16x32_bf16 v[54:57], v[158:161], v[218:221], v[54:57]
	v_mfma_f32_16x16x32_bf16 v[46:49], v[166:169], v[218:221], v[46:49]
	v_mfma_f32_16x16x32_bf16 v[38:41], v[158:161], v[226:229], v[38:41]
	v_mfma_f32_16x16x32_bf16 v[30:33], v[166:169], v[226:229], v[30:33]
	v_mfma_f32_16x16x32_bf16 v[22:25], v[158:161], v[234:237], v[22:25]
	v_mfma_f32_16x16x32_bf16 v[14:17], v[166:169], v[234:237], v[14:17]
	v_mfma_f32_16x16x32_bf16 v[62:65], v[162:165], v[198:201], v[62:65]
	v_mfma_f32_16x16x32_bf16 v[58:61], v[170:173], v[198:201], v[58:61]
	v_mfma_f32_16x16x32_bf16 v[54:57], v[162:165], v[222:225], v[54:57]
	v_mfma_f32_16x16x32_bf16 v[46:49], v[170:173], v[222:225], v[46:49]
	v_mfma_f32_16x16x32_bf16 v[38:41], v[162:165], v[230:233], v[38:41]
	v_mfma_f32_16x16x32_bf16 v[30:33], v[170:173], v[230:233], v[30:33]
	v_mfma_f32_16x16x32_bf16 v[22:25], v[162:165], v[238:241], v[22:25]
	v_mfma_f32_16x16x32_bf16 v[14:17], v[170:173], v[238:241], v[14:17]
	v_mfma_f32_16x16x32_bf16 v[50:53], v[174:177], v[190:193], v[50:53]
	v_mfma_f32_16x16x32_bf16 v[42:45], v[182:185], v[190:193], v[42:45]
	v_mfma_f32_16x16x32_bf16 v[34:37], v[174:177], v[218:221], v[34:37]
	v_mfma_f32_16x16x32_bf16 v[26:29], v[182:185], v[218:221], v[26:29]
	v_mfma_f32_16x16x32_bf16 v[18:21], v[174:177], v[226:229], v[18:21]
	v_mfma_f32_16x16x32_bf16 v[10:13], v[182:185], v[226:229], v[10:13]
	v_mfma_f32_16x16x32_bf16 v[6:9], v[174:177], v[234:237], v[6:9]
	v_mfma_f32_16x16x32_bf16 v[2:5], v[182:185], v[234:237], v[2:5]
	v_mfma_f32_16x16x32_bf16 v[50:53], v[178:181], v[198:201], v[50:53]
	v_mfma_f32_16x16x32_bf16 v[42:45], v[186:189], v[198:201], v[42:45]
	v_mfma_f32_16x16x32_bf16 v[34:37], v[178:181], v[222:225], v[34:37]
	v_mfma_f32_16x16x32_bf16 v[26:29], v[186:189], v[222:225], v[26:29]
	v_mfma_f32_16x16x32_bf16 v[18:21], v[178:181], v[230:233], v[18:21]
	v_mfma_f32_16x16x32_bf16 v[10:13], v[186:189], v[230:233], v[10:13]
	v_mfma_f32_16x16x32_bf16 v[6:9], v[178:181], v[238:241], v[6:9]
	v_mfma_f32_16x16x32_bf16 v[2:5], v[186:189], v[238:241], v[2:5]
	s_setprio 0
	s_barrier
	s_add_i32 s96, 0, 0x18000
	v_add_u32_e32 v157, s96, v145
	s_add_i32 s97, 0, 0x1c000
	ds_read_b128 v[158:161], v157
	ds_read_b128 v[162:165], v157 offset:1024
	ds_read_b128 v[166:169], v157 offset:2048
	ds_read_b128 v[170:173], v157 offset:3072
	v_add_u32_e32 v157, s97, v145
	ds_read_b128 v[174:177], v157
	ds_read_b128 v[178:181], v157 offset:1024
	ds_read_b128 v[182:185], v157 offset:2048
	ds_read_b128 v[186:189], v157 offset:3072
	s_add_u32 s12, s16, 0x2c0000
	s_addc_u32 s13, s17, 0
	s_mov_b32 m0, s40
	v_lshl_add_u64 v[202:203], s[12:13], 0, v[130:131]
	ds_read_b128 v[190:193], v153 offset:32768
	ds_read_b128 v[198:201], v153 offset:33792
	ds_read_b128 v[218:221], v153 offset:34816
	ds_read_b128 v[222:225], v153 offset:35840
	ds_read_b128 v[226:229], v153 offset:36864
	ds_read_b128 v[230:233], v153 offset:37888
	ds_read_b128 v[234:237], v153 offset:38912
	ds_read_b128 v[238:241], v153 offset:39936
	global_load_lds_dwordx4 v[202:203], off
	v_lshl_add_u64 v[202:203], s[12:13], 0, v[134:135]
	s_mov_b32 m0, s41
	s_nop 0
	global_load_lds_dwordx4 v[202:203], off
	s_waitcnt vmcnt(8) lgkmcnt(0)
	s_barrier
	s_setprio 1
	v_mfma_f32_16x16x32_bf16 v[126:129], v[158:161], v[190:193], v[126:129]
	v_mfma_f32_16x16x32_bf16 v[122:125], v[166:169], v[190:193], v[122:125]
	v_mfma_f32_16x16x32_bf16 v[118:121], v[158:161], v[218:221], v[118:121]
	v_mfma_f32_16x16x32_bf16 v[110:113], v[166:169], v[218:221], v[110:113]
	v_mfma_f32_16x16x32_bf16 v[102:105], v[158:161], v[226:229], v[102:105]
	v_mfma_f32_16x16x32_bf16 v[94:97], v[166:169], v[226:229], v[94:97]
	v_mfma_f32_16x16x32_bf16 v[86:89], v[158:161], v[234:237], v[86:89]
	v_mfma_f32_16x16x32_bf16 v[78:81], v[166:169], v[234:237], v[78:81]
	v_mfma_f32_16x16x32_bf16 v[126:129], v[162:165], v[198:201], v[126:129]
	v_mfma_f32_16x16x32_bf16 v[122:125], v[170:173], v[198:201], v[122:125]
	v_mfma_f32_16x16x32_bf16 v[118:121], v[162:165], v[222:225], v[118:121]
	v_mfma_f32_16x16x32_bf16 v[110:113], v[170:173], v[222:225], v[110:113]
	v_mfma_f32_16x16x32_bf16 v[102:105], v[162:165], v[230:233], v[102:105]
	v_mfma_f32_16x16x32_bf16 v[94:97], v[170:173], v[230:233], v[94:97]
	v_mfma_f32_16x16x32_bf16 v[86:89], v[162:165], v[238:241], v[86:89]
	v_mfma_f32_16x16x32_bf16 v[78:81], v[170:173], v[238:241], v[78:81]
	v_mfma_f32_16x16x32_bf16 v[114:117], v[174:177], v[190:193], v[114:117]
	v_mfma_f32_16x16x32_bf16 v[106:109], v[182:185], v[190:193], v[106:109]
	v_mfma_f32_16x16x32_bf16 v[98:101], v[174:177], v[218:221], v[98:101]
	v_mfma_f32_16x16x32_bf16 v[90:93], v[182:185], v[218:221], v[90:93]
	v_mfma_f32_16x16x32_bf16 v[82:85], v[174:177], v[226:229], v[82:85]
	v_mfma_f32_16x16x32_bf16 v[74:77], v[182:185], v[226:229], v[74:77]
	v_mfma_f32_16x16x32_bf16 v[70:73], v[174:177], v[234:237], v[70:73]
	v_mfma_f32_16x16x32_bf16 v[66:69], v[182:185], v[234:237], v[66:69]
	v_mfma_f32_16x16x32_bf16 v[114:117], v[178:181], v[198:201], v[114:117]
	v_mfma_f32_16x16x32_bf16 v[106:109], v[186:189], v[198:201], v[106:109]
	v_mfma_f32_16x16x32_bf16 v[98:101], v[178:181], v[222:225], v[98:101]
	v_mfma_f32_16x16x32_bf16 v[90:93], v[186:189], v[222:225], v[90:93]
	v_mfma_f32_16x16x32_bf16 v[82:85], v[178:181], v[230:233], v[82:85]
	v_mfma_f32_16x16x32_bf16 v[74:77], v[186:189], v[230:233], v[74:77]
	v_mfma_f32_16x16x32_bf16 v[70:73], v[178:181], v[238:241], v[70:73]
	v_mfma_f32_16x16x32_bf16 v[66:69], v[186:189], v[238:241], v[66:69]
	s_setprio 0
	s_barrier
; #define PG8_STAGE(bufoff, gbase, voff) do { _Pragma("unroll") for (int _i = 0; _i < 2; ++_i) \
;         __builtin_amdgcn_global_load_lds((const unsigned*)((const char*)(gbase) + (voff)[_i]), (PG8_LAS unsigned*)(lds + (bufoff) + ldsw + _i * 8192), 16, 0, 0); } while (0)
; #define PG8_LDA(dst, b, h) do { _Pragma("unroll") for (int m = 0; m < 4; ++m) _Pragma("unroll") for (int k = 0; k < 2; ++k) dst[m][k] = *(const PG8_LAS bf16x8*)(lds + PG8_SA(b, h) + aoff + m * 2048 + k * 1024); } while (0)
; #define PG8_MMA(ai, bj, At, Bt) do { __builtin_amdgcn_s_setprio(1); _Pragma("unroll") for (int m = 0; m < 4; ++m) _Pragma("unroll") for (int n = 0; n < 2; ++n) _Pragma("unroll") for (int k = 0; k < 2; ++k) \
;         acc[ai][bj][m][n] = __builtin_amdgcn_mfma_f32_16x16x32_bf16(Bt[n][k], At[m][k], acc[ai][bj][m][n], 0, 0, 0); __builtin_amdgcn_s_setprio(0); } while (0)
; #define PG8_WAIT_V(n) asm volatile("s_waitcnt vmcnt(" #n ")" ::: "memory")
; #define PG8_WAIT_L(n) asm volatile("s_waitcnt lgkmcnt(" #n ")" ::: "memory")
; #define PG8_BAR __builtin_amdgcn_s_barrier()
; #define PG8_SCHED __builtin_amdgcn_sched_barrier(0)
; template <class Epi, class Sched, bool ALIGN_EPI = false, bool SP2 = false>
; __device__ __forceinline__ void gemm_phase(PG8_LAS unsigned char* lds, const Gemm g, const Sched& S, const Epi& E, int wv) {
;     ...
;         for (int t = 0; t < nt; t += 2) {
;             const bool last = (t == nt - 2);
;     ...
;             PG8_LDA(At, 1, 1); PG8_STAGE(PG8_SB(1, 0), b3, voffB); PG8_STAGE(PG8_SB(1, 1), b3 + hstepB, voffB); PG8_STAGE(PG8_SA(1, 0), a3, voffA);
;             PG8_WAIT_V(8); PG8_WAIT_L(0); PG8_BAR; PG8_MMA(1, 0, At, B0); PG8_MMA(1, 1, At, B1); PG8_BAR; PG8_SCHED;
	s_add_i32 s12, s96, s30
	v_lshl_add_u64 v[142:143], v[142:143], 0, s[20:21]
	s_mov_b32 m0, s12
	ds_read_b128 v[190:193], v153 offset:49152
	ds_read_b128 v[198:201], v153 offset:50176
	ds_read_b128 v[218:221], v153 offset:51200
	ds_read_b128 v[222:225], v153 offset:52224
	ds_read_b128 v[226:229], v153 offset:53248
	ds_read_b128 v[230:233], v153 offset:54272
	ds_read_b128 v[234:237], v153 offset:55296
	ds_read_b128 v[238:241], v153 offset:56320
	global_load_lds_dwordx4 v[142:143], off
	s_add_i32 m0, s12, 0x2000
	s_add_u32 s12, s14, 0x100080
	v_lshl_add_u64 v[142:143], v[154:155], 0, s[20:21]
	s_addc_u32 s13, s15, 0
	s_add_i32 s14, s97, s30
	global_load_lds_dwordx4 v[142:143], off
	v_lshl_add_u64 v[142:143], s[12:13], 0, v[132:133]
	s_mov_b32 m0, s14
	s_nop 0
	global_load_lds_dwordx4 v[142:143], off
	v_lshl_add_u64 v[142:143], s[12:13], 0, v[136:137]
	s_add_i32 m0, s14, 0x2000
	s_nop 0
	global_load_lds_dwordx4 v[142:143], off
	v_lshl_add_u64 v[142:143], v[194:195], 0, s[20:21]
	s_mov_b32 m0, s43
	s_nop 0
	global_load_lds_dwordx4 v[142:143], off
	v_lshl_add_u64 v[142:143], v[196:197], 0, s[20:21]
	s_mov_b32 m0, s65
	s_nop 0
	global_load_lds_dwordx4 v[142:143], off
	s_waitcnt vmcnt(8) lgkmcnt(0)
	s_barrier
	s_setprio 1
	v_mfma_f32_16x16x32_bf16 v[62:65], v[158:161], v[190:193], v[62:65]
	v_mfma_f32_16x16x32_bf16 v[58:61], v[166:169], v[190:193], v[58:61]
	v_mfma_f32_16x16x32_bf16 v[54:57], v[158:161], v[218:221], v[54:57]
	v_mfma_f32_16x16x32_bf16 v[46:49], v[166:169], v[218:221], v[46:49]
	v_mfma_f32_16x16x32_bf16 v[38:41], v[158:161], v[226:229], v[38:41]
	v_mfma_f32_16x16x32_bf16 v[30:33], v[166:169], v[226:229], v[30:33]
	v_mfma_f32_16x16x32_bf16 v[22:25], v[158:161], v[234:237], v[22:25]
	v_mfma_f32_16x16x32_bf16 v[14:17], v[166:169], v[234:237], v[14:17]
	v_mfma_f32_16x16x32_bf16 v[62:65], v[162:165], v[198:201], v[62:65]
	v_mfma_f32_16x16x32_bf16 v[58:61], v[170:173], v[198:201], v[58:61]
	v_mfma_f32_16x16x32_bf16 v[54:57], v[162:165], v[222:225], v[54:57]
	v_mfma_f32_16x16x32_bf16 v[46:49], v[170:173], v[222:225], v[46:49]
	v_mfma_f32_16x16x32_bf16 v[38:41], v[162:165], v[230:233], v[38:41]
	v_mfma_f32_16x16x32_bf16 v[30:33], v[170:173], v[230:233], v[30:33]
	v_mfma_f32_16x16x32_bf16 v[22:25], v[162:165], v[238:241], v[22:25]
	v_mfma_f32_16x16x32_bf16 v[14:17], v[170:173], v[238:241], v[14:17]
	v_mfma_f32_16x16x32_bf16 v[50:53], v[174:177], v[190:193], v[50:53]
	v_mfma_f32_16x16x32_bf16 v[42:45], v[182:185], v[190:193], v[42:45]
	v_mfma_f32_16x16x32_bf16 v[34:37], v[174:177], v[218:221], v[34:37]
	v_mfma_f32_16x16x32_bf16 v[26:29], v[182:185], v[218:221], v[26:29]
	v_mfma_f32_16x16x32_bf16 v[18:21], v[174:177], v[226:229], v[18:21]
	v_mfma_f32_16x16x32_bf16 v[10:13], v[182:185], v[226:229], v[10:13]
	v_mfma_f32_16x16x32_bf16 v[6:9], v[174:177], v[234:237], v[6:9]
	v_mfma_f32_16x16x32_bf16 v[2:5], v[182:185], v[234:237], v[2:5]
	v_mfma_f32_16x16x32_bf16 v[50:53], v[178:181], v[198:201], v[50:53]
	v_mfma_f32_16x16x32_bf16 v[42:45], v[186:189], v[198:201], v[42:45]
	v_mfma_f32_16x16x32_bf16 v[34:37], v[178:181], v[222:225], v[34:37]
	v_mfma_f32_16x16x32_bf16 v[26:29], v[186:189], v[222:225], v[26:29]
	v_mfma_f32_16x16x32_bf16 v[18:21], v[178:181], v[230:233], v[18:21]
	v_mfma_f32_16x16x32_bf16 v[10:13], v[186:189], v[230:233], v[10:13]
	v_mfma_f32_16x16x32_bf16 v[6:9], v[178:181], v[238:241], v[6:9]
	v_mfma_f32_16x16x32_bf16 v[2:5], v[186:189], v[238:241], v[2:5]
	s_setprio 0
	s_barrier
	s_add_i32 s79, s79, 2
	s_add_u32 s76, s76, 0x100
	s_addc_u32 s77, s77, 0
	s_cmp_gt_u32 s79, 61
	s_mov_b64 s[12:13], s[0:1]
	s_cbranch_scc0 .LBB0_59
	s_and_b64 vcc, exec, s[4:5]
	s_cbranch_vccz .LBB0_62
	s_barrier

; #define PG8_STAGE(bufoff, gbase, voff) do { _Pragma("unroll") for (int _i = 0; _i < 2; ++_i) \
;         __builtin_amdgcn_global_load_lds((const unsigned*)((const char*)(gbase) + (voff)[_i]), (PG8_LAS unsigned*)(lds + (bufoff) + ldsw + _i * 8192), 16, 0, 0); } while (0)
; #define PG8_LDA(dst, b, h) do { _Pragma("unroll") for (int m = 0; m < 4; ++m) _Pragma("unroll") for (int k = 0; k < 2; ++k) dst[m][k] = *(const PG8_LAS bf16x8*)(lds + PG8_SA(b, h) + aoff + m * 2048 + k * 1024); } while (0)
; #define PG8_LDB(dst, b, h) do { _Pragma("unroll") for (int n = 0; n < 2; ++n) _Pragma("unroll") for (int k = 0; k < 2; ++k) dst[n][k] = *(const PG8_LAS bf16x8*)(lds + PG8_SB(b, h) + boff + n * 2048 + k * 1024); } while (0)
; #define PG8_MMA(ai, bj, At, Bt) do { __builtin_amdgcn_s_setprio(1); _Pragma("unroll") for (int m = 0; m < 4; ++m) _Pragma("unroll") for (int n = 0; n < 2; ++n) _Pragma("unroll") for (int k = 0; k < 2; ++k) \
;         acc[ai][bj][m][n] = __builtin_amdgcn_mfma_f32_16x16x32_bf16(Bt[n][k], At[m][k], acc[ai][bj][m][n], 0, 0, 0); __builtin_amdgcn_s_setprio(0); } while (0)
; #define PG8_WAIT_V(n) asm volatile("s_waitcnt vmcnt(" #n ")" ::: "memory")
; #define PG8_WAIT_L(n) asm volatile("s_waitcnt lgkmcnt(" #n ")" ::: "memory")
; #define PG8_BAR __builtin_amdgcn_s_barrier()
; #define PG8_SCHED __builtin_amdgcn_sched_barrier(0)
; template <class Epi, class Sched, bool ALIGN_EPI = false, bool SP2 = false>
; __device__ __forceinline__ void gemm_phase(PG8_LAS unsigned char* lds, const Gemm g, const Sched& S, const Epi& E, int wv) {
;     ...
;             const bool last = (t == nt - 2);
;             const char* a1 = cA + (size_t)(t + 1) * kstep;
;             const char* a2 = last ? nA : cA + (size_t)(t + 2) * kstep; const char* b2 = last ? nB : cB + (size_t)(t + 2) * kstep;
;             const char* a3 = a2 + kstep; const char* b3 = b2 + kstep;
;             if (last && has_next) S.a_ready(nxt);
;             if constexpr (SP2) {
;             PG8_LDB(B0, 0, 0); PG8_LDB(B1, 0, 1); PG8_SCHED; PG8_LDA(At, 0, 0); PG8_STAGE(PG8_SA(1, 1), a1 + hstepA, voffA);
;             PG8_WAIT_V(8); PG8_WAIT_L(0); PG8_BAR; PG8_MMA(0, 0, At, B0); PG8_MMA(0, 1, At, B1); PG8_BAR; PG8_SCHED;
;             PG8_LDA(At, 0, 1); PG8_STAGE(PG8_SB(0, 0), b2, voffB); PG8_STAGE(PG8_SB(0, 1), b2 + hstepB, voffB); PG8_STAGE(PG8_SA(0, 0), a2, voffA);
.LBB0_86:
	s_add_u32 s16, s14, 0xfffc0080
	s_addc_u32 s17, s15, -1
	s_add_i32 s96, 0, 0x10000
	s_cmp_eq_u32 s79, 12
	s_cselect_b32 s19, s7, s17
	s_cselect_b32 s18, s74, s16
	v_add_u32_e32 v142, s96, v145
	s_cselect_b32 s17, s5, s77
	s_cselect_b32 s16, s75, s76
	s_add_i32 vcc_lo, 0, 0x14000
	ds_read_b128 v[148:151], v142
	ds_read_b128 v[152:155], v142 offset:1024
	ds_read_b128 v[158:161], v142 offset:2048
	ds_read_b128 v[162:165], v142 offset:3072
	v_add_u32_e32 v142, vcc_lo, v145
	ds_read_b128 v[166:169], v142
	ds_read_b128 v[170:173], v142 offset:1024
	ds_read_b128 v[174:177], v142 offset:2048
	ds_read_b128 v[178:181], v142 offset:3072
	v_lshl_add_u64 v[142:143], s[14:15], 0, v[138:139]
	s_add_i32 m0, s40, 0xc000
	ds_read_b128 v[182:185], v146
	ds_read_b128 v[186:189], v146 offset:1024
	ds_read_b128 v[190:193], v146 offset:2048
	ds_read_b128 v[198:201], v146 offset:3072
	ds_read_b128 v[218:221], v146 offset:4096
	ds_read_b128 v[222:225], v146 offset:5120
	ds_read_b128 v[226:229], v146 offset:6144
	ds_read_b128 v[230:233], v146 offset:7168
	global_load_lds_dwordx4 v[142:143], off
	v_lshl_add_u64 v[142:143], s[14:15], 0, v[140:141]
	s_add_i32 m0, s40, 0xe000
	s_nop 0
	global_load_lds_dwordx4 v[142:143], off
	s_waitcnt vmcnt(8) lgkmcnt(0)
	s_barrier
	s_setprio 1
	v_mfma_f32_16x16x32_bf16 v[126:129], v[148:151], v[182:185], v[126:129]
	v_mfma_f32_16x16x32_bf16 v[122:125], v[158:161], v[182:185], v[122:125]
	v_mfma_f32_16x16x32_bf16 v[110:113], v[148:151], v[190:193], v[110:113]
	v_mfma_f32_16x16x32_bf16 v[106:109], v[158:161], v[190:193], v[106:109]
	v_mfma_f32_16x16x32_bf16 v[94:97], v[148:151], v[218:221], v[94:97]
	v_mfma_f32_16x16x32_bf16 v[90:93], v[158:161], v[218:221], v[90:93]
	v_mfma_f32_16x16x32_bf16 v[78:81], v[148:151], v[226:229], v[78:81]
	v_mfma_f32_16x16x32_bf16 v[74:77], v[158:161], v[226:229], v[74:77]
	v_mfma_f32_16x16x32_bf16 v[126:129], v[152:155], v[186:189], v[126:129]
	v_mfma_f32_16x16x32_bf16 v[122:125], v[162:165], v[186:189], v[122:125]
	v_mfma_f32_16x16x32_bf16 v[110:113], v[152:155], v[198:201], v[110:113]
	v_mfma_f32_16x16x32_bf16 v[106:109], v[162:165], v[198:201], v[106:109]
	v_mfma_f32_16x16x32_bf16 v[94:97], v[152:155], v[222:225], v[94:97]
	v_mfma_f32_16x16x32_bf16 v[90:93], v[162:165], v[222:225], v[90:93]
	v_mfma_f32_16x16x32_bf16 v[78:81], v[152:155], v[230:233], v[78:81]
	v_mfma_f32_16x16x32_bf16 v[74:77], v[162:165], v[230:233], v[74:77]
	v_mfma_f32_16x16x32_bf16 v[118:121], v[166:169], v[182:185], v[118:121]
	v_mfma_f32_16x16x32_bf16 v[114:117], v[174:177], v[182:185], v[114:117]
	v_mfma_f32_16x16x32_bf16 v[102:105], v[166:169], v[190:193], v[102:105]
	v_mfma_f32_16x16x32_bf16 v[98:101], v[174:177], v[190:193], v[98:101]
	v_mfma_f32_16x16x32_bf16 v[86:89], v[166:169], v[218:221], v[86:89]
	v_mfma_f32_16x16x32_bf16 v[82:85], v[174:177], v[218:221], v[82:85]
	v_mfma_f32_16x16x32_bf16 v[70:73], v[166:169], v[226:229], v[70:73]
	v_mfma_f32_16x16x32_bf16 v[66:69], v[174:177], v[226:229], v[66:69]
	v_mfma_f32_16x16x32_bf16 v[118:121], v[170:173], v[186:189], v[118:121]
	v_mfma_f32_16x16x32_bf16 v[114:117], v[178:181], v[186:189], v[114:117]
	v_mfma_f32_16x16x32_bf16 v[102:105], v[170:173], v[198:201], v[102:105]
	v_mfma_f32_16x16x32_bf16 v[98:101], v[178:181], v[198:201], v[98:101]
	v_mfma_f32_16x16x32_bf16 v[86:89], v[170:173], v[222:225], v[86:89]
	v_mfma_f32_16x16x32_bf16 v[82:85], v[178:181], v[222:225], v[82:85]
	v_mfma_f32_16x16x32_bf16 v[70:73], v[170:173], v[230:233], v[70:73]
	v_mfma_f32_16x16x32_bf16 v[66:69], v[178:181], v[230:233], v[66:69]
	s_setprio 0
	s_barrier
	s_add_i32 s96, s96, s33
	v_lshl_add_u64 v[142:143], s[16:17], 0, v[132:133]
	s_mov_b32 m0, s96
	ds_read_b128 v[182:185], v146 offset:16384
	ds_read_b128 v[186:189], v146 offset:17408
	ds_read_b128 v[190:193], v146 offset:18432
	ds_read_b128 v[198:201], v146 offset:19456
	ds_read_b128 v[218:221], v146 offset:20480
	ds_read_b128 v[222:225], v146 offset:21504
	ds_read_b128 v[226:229], v146 offset:22528
	ds_read_b128 v[230:233], v146 offset:23552
	global_load_lds_dwordx4 v[142:143], off
	s_add_i32 m0, s96, 0x2000
	s_add_u32 s96, s16, 0x40000
	v_lshl_add_u64 v[194:195], s[16:17], 0, v[136:137]
	s_addc_u32 s97, s17, 0
	s_add_i32 vcc_lo, vcc_lo, s33
	global_load_lds_dwordx4 v[194:195], off
	v_lshl_add_u64 v[196:197], s[96:97], 0, v[132:133]
	s_mov_b32 m0, vcc_lo
	v_lshl_add_u64 v[202:203], s[18:19], 0, v[134:135]
	global_load_lds_dwordx4 v[196:197], off
	v_lshl_add_u64 v[196:197], s[96:97], 0, v[136:137]
	s_add_i32 m0, vcc_lo, 0x2000
	s_nop 0
	global_load_lds_dwordx4 v[196:197], off
	v_lshl_add_u64 v[196:197], s[18:19], 0, v[130:131]
	s_mov_b32 m0, s40
	s_nop 0
	global_load_lds_dwordx4 v[196:197], off
	s_mov_b32 m0, s41
	s_nop 0
	global_load_lds_dwordx4 v[202:203], off
	s_waitcnt vmcnt(8) lgkmcnt(0)
	s_barrier
; #define PG8_STAGE(bufoff, gbase, voff) do { _Pragma("unroll") for (int _i = 0; _i < 2; ++_i) \
;         __builtin_amdgcn_global_load_lds((const unsigned*)((const char*)(gbase) + (voff)[_i]), (PG8_LAS unsigned*)(lds + (bufoff) + ldsw + _i * 8192), 16, 0, 0); } while (0)
; #define PG8_LDA(dst, b, h) do { _Pragma("unroll") for (int m = 0; m < 4; ++m) _Pragma("unroll") for (int k = 0; k < 2; ++k) dst[m][k] = *(const PG8_LAS bf16x8*)(lds + PG8_SA(b, h) + aoff + m * 2048 + k * 1024); } while (0)
; #define PG8_LDB(dst, b, h) do { _Pragma("unroll") for (int n = 0; n < 2; ++n) _Pragma("unroll") for (int k = 0; k < 2; ++k) dst[n][k] = *(const PG8_LAS bf16x8*)(lds + PG8_SB(b, h) + boff + n * 2048 + k * 1024); } while (0)
; #define PG8_MMA(ai, bj, At, Bt) do { __builtin_amdgcn_s_setprio(1); _Pragma("unroll") for (int m = 0; m < 4; ++m) _Pragma("unroll") for (int n = 0; n < 2; ++n) _Pragma("unroll") for (int k = 0; k < 2; ++k) \
;         acc[ai][bj][m][n] = __builtin_amdgcn_mfma_f32_16x16x32_bf16(Bt[n][k], At[m][k], acc[ai][bj][m][n], 0, 0, 0); __builtin_amdgcn_s_setprio(0); } while (0)
; #define PG8_WAIT_V(n) asm volatile("s_waitcnt vmcnt(" #n ")" ::: "memory")
; #define PG8_WAIT_L(n) asm volatile("s_waitcnt lgkmcnt(" #n ")" ::: "memory")
; #define PG8_BAR __builtin_amdgcn_s_barrier()
; #define PG8_SCHED __builtin_amdgcn_sched_barrier(0)
; template <class Epi, class Sched, bool ALIGN_EPI = false, bool SP2 = false>
; __device__ __forceinline__ void gemm_phase(PG8_LAS unsigned char* lds, const Gemm g, const Sched& S, const Epi& E, int wv) {
;     ...
;             PG8_WAIT_V(8); PG8_WAIT_L(0); PG8_BAR; PG8_MMA(1, 0, At, B0); PG8_MMA(1, 1, At, B1); PG8_BAR; PG8_SCHED;
;             PG8_LDB(B0, 1, 0); PG8_LDB(B1, 1, 1); PG8_SCHED; PG8_LDA(At, 1, 0); PG8_STAGE(PG8_SA(0, 1), a2 + hstepA, voffA);
;             PG8_WAIT_V(8); PG8_WAIT_L(0); PG8_BAR; PG8_MMA(0, 0, At, B0); PG8_MMA(0, 1, At, B1); PG8_BAR; PG8_SCHED;
	s_setprio 1
	v_mfma_f32_16x16x32_bf16 v[62:65], v[148:151], v[182:185], v[62:65]
	v_mfma_f32_16x16x32_bf16 v[58:61], v[158:161], v[182:185], v[58:61]
	v_mfma_f32_16x16x32_bf16 v[46:49], v[148:151], v[190:193], v[46:49]
	v_mfma_f32_16x16x32_bf16 v[42:45], v[158:161], v[190:193], v[42:45]
	v_mfma_f32_16x16x32_bf16 v[30:33], v[148:151], v[218:221], v[30:33]
	v_mfma_f32_16x16x32_bf16 v[26:29], v[158:161], v[218:221], v[26:29]
	v_mfma_f32_16x16x32_bf16 v[14:17], v[148:151], v[226:229], v[14:17]
	v_mfma_f32_16x16x32_bf16 v[10:13], v[158:161], v[226:229], v[10:13]
	v_mfma_f32_16x16x32_bf16 v[62:65], v[152:155], v[186:189], v[62:65]
	v_mfma_f32_16x16x32_bf16 v[58:61], v[162:165], v[186:189], v[58:61]
	v_mfma_f32_16x16x32_bf16 v[46:49], v[152:155], v[198:201], v[46:49]
	v_mfma_f32_16x16x32_bf16 v[42:45], v[162:165], v[198:201], v[42:45]
	v_mfma_f32_16x16x32_bf16 v[30:33], v[152:155], v[222:225], v[30:33]
	v_mfma_f32_16x16x32_bf16 v[26:29], v[162:165], v[222:225], v[26:29]
	v_mfma_f32_16x16x32_bf16 v[14:17], v[152:155], v[230:233], v[14:17]
	v_mfma_f32_16x16x32_bf16 v[10:13], v[162:165], v[230:233], v[10:13]
	v_mfma_f32_16x16x32_bf16 v[54:57], v[166:169], v[182:185], v[54:57]
	v_mfma_f32_16x16x32_bf16 v[50:53], v[174:177], v[182:185], v[50:53]
	v_mfma_f32_16x16x32_bf16 v[38:41], v[166:169], v[190:193], v[38:41]
	v_mfma_f32_16x16x32_bf16 v[34:37], v[174:177], v[190:193], v[34:37]
	v_mfma_f32_16x16x32_bf16 v[22:25], v[166:169], v[218:221], v[22:25]
	v_mfma_f32_16x16x32_bf16 v[18:21], v[174:177], v[218:221], v[18:21]
	v_mfma_f32_16x16x32_bf16 v[6:9], v[166:169], v[226:229], v[6:9]
	v_mfma_f32_16x16x32_bf16 v[2:5], v[174:177], v[226:229], v[2:5]
	v_mfma_f32_16x16x32_bf16 v[54:57], v[170:173], v[186:189], v[54:57]
	v_mfma_f32_16x16x32_bf16 v[50:53], v[178:181], v[186:189], v[50:53]
	v_mfma_f32_16x16x32_bf16 v[38:41], v[170:173], v[198:201], v[38:41]
	v_mfma_f32_16x16x32_bf16 v[34:37], v[178:181], v[198:201], v[34:37]
	v_mfma_f32_16x16x32_bf16 v[22:25], v[170:173], v[222:225], v[22:25]
	v_mfma_f32_16x16x32_bf16 v[18:21], v[178:181], v[222:225], v[18:21]
	v_mfma_f32_16x16x32_bf16 v[6:9], v[170:173], v[230:233], v[6:9]
	v_mfma_f32_16x16x32_bf16 v[2:5], v[178:181], v[230:233], v[2:5]
	s_setprio 0
	s_barrier
	s_add_i32 s96, 0, 0x18000
	v_add_u32_e32 v147, s96, v145
	s_add_i32 s97, 0, 0x1c000
	ds_read_b128 v[148:151], v147
	ds_read_b128 v[152:155], v147 offset:1024
	ds_read_b128 v[158:161], v147 offset:2048
	ds_read_b128 v[162:165], v147 offset:3072
	v_add_u32_e32 v147, s97, v145
	ds_read_b128 v[166:169], v147
	ds_read_b128 v[170:173], v147 offset:1024
	ds_read_b128 v[174:177], v147 offset:2048
	ds_read_b128 v[178:181], v147 offset:3072
	s_add_u32 s18, s18, 0x40000
	s_addc_u32 s19, s19, 0
	s_mov_b32 m0, s42
	v_lshl_add_u64 v[204:205], s[18:19], 0, v[130:131]
	ds_read_b128 v[182:185], v146 offset:32768
	ds_read_b128 v[186:189], v146 offset:33792
	ds_read_b128 v[190:193], v146 offset:34816
	ds_read_b128 v[198:201], v146 offset:35840
	ds_read_b128 v[218:221], v146 offset:36864
	ds_read_b128 v[222:225], v146 offset:37888
	ds_read_b128 v[226:229], v146 offset:38912
	ds_read_b128 v[230:233], v146 offset:39936
	global_load_lds_dwordx4 v[204:205], off
	v_lshl_add_u64 v[204:205], s[18:19], 0, v[134:135]
	s_mov_b32 m0, s43
	s_nop 0
	global_load_lds_dwordx4 v[204:205], off
	s_waitcnt vmcnt(8) lgkmcnt(0)
	s_barrier
	s_setprio 1
	v_mfma_f32_16x16x32_bf16 v[126:129], v[148:151], v[182:185], v[126:129]
	v_mfma_f32_16x16x32_bf16 v[122:125], v[158:161], v[182:185], v[122:125]
	v_mfma_f32_16x16x32_bf16 v[110:113], v[148:151], v[190:193], v[110:113]
	v_mfma_f32_16x16x32_bf16 v[106:109], v[158:161], v[190:193], v[106:109]
	v_mfma_f32_16x16x32_bf16 v[94:97], v[148:151], v[218:221], v[94:97]
	v_mfma_f32_16x16x32_bf16 v[90:93], v[158:161], v[218:221], v[90:93]
	v_mfma_f32_16x16x32_bf16 v[78:81], v[148:151], v[226:229], v[78:81]
	v_mfma_f32_16x16x32_bf16 v[74:77], v[158:161], v[226:229], v[74:77]
	v_mfma_f32_16x16x32_bf16 v[126:129], v[152:155], v[186:189], v[126:129]
	v_mfma_f32_16x16x32_bf16 v[122:125], v[162:165], v[186:189], v[122:125]
	v_mfma_f32_16x16x32_bf16 v[110:113], v[152:155], v[198:201], v[110:113]
	v_mfma_f32_16x16x32_bf16 v[106:109], v[162:165], v[198:201], v[106:109]
	v_mfma_f32_16x16x32_bf16 v[94:97], v[152:155], v[222:225], v[94:97]
	v_mfma_f32_16x16x32_bf16 v[90:93], v[162:165], v[222:225], v[90:93]
	v_mfma_f32_16x16x32_bf16 v[78:81], v[152:155], v[230:233], v[78:81]
	v_mfma_f32_16x16x32_bf16 v[74:77], v[162:165], v[230:233], v[74:77]
	v_mfma_f32_16x16x32_bf16 v[118:121], v[166:169], v[182:185], v[118:121]
	v_mfma_f32_16x16x32_bf16 v[114:117], v[174:177], v[182:185], v[114:117]
	v_mfma_f32_16x16x32_bf16 v[102:105], v[166:169], v[190:193], v[102:105]
	v_mfma_f32_16x16x32_bf16 v[98:101], v[174:177], v[190:193], v[98:101]
	v_mfma_f32_16x16x32_bf16 v[86:89], v[166:169], v[218:221], v[86:89]
	v_mfma_f32_16x16x32_bf16 v[82:85], v[174:177], v[218:221], v[82:85]
	v_mfma_f32_16x16x32_bf16 v[70:73], v[166:169], v[226:229], v[70:73]
	v_mfma_f32_16x16x32_bf16 v[66:69], v[174:177], v[226:229], v[66:69]
	v_mfma_f32_16x16x32_bf16 v[118:121], v[170:173], v[186:189], v[118:121]
	v_mfma_f32_16x16x32_bf16 v[114:117], v[178:181], v[186:189], v[114:117]
	v_mfma_f32_16x16x32_bf16 v[102:105], v[170:173], v[198:201], v[102:105]
	v_mfma_f32_16x16x32_bf16 v[98:101], v[178:181], v[198:201], v[98:101]
	v_mfma_f32_16x16x32_bf16 v[86:89], v[170:173], v[222:225], v[86:89]
	v_mfma_f32_16x16x32_bf16 v[82:85], v[178:181], v[222:225], v[82:85]
	v_mfma_f32_16x16x32_bf16 v[70:73], v[170:173], v[230:233], v[70:73]
	v_mfma_f32_16x16x32_bf16 v[66:69], v[178:181], v[230:233], v[66:69]
	s_setprio 0
	s_barrier
; #define PG8_STAGE(bufoff, gbase, voff) do { _Pragma("unroll") for (int _i = 0; _i < 2; ++_i) \
;         __builtin_amdgcn_global_load_lds((const unsigned*)((const char*)(gbase) + (voff)[_i]), (PG8_LAS unsigned*)(lds + (bufoff) + ldsw + _i * 8192), 16, 0, 0); } while (0)
; #define PG8_LDA(dst, b, h) do { _Pragma("unroll") for (int m = 0; m < 4; ++m) _Pragma("unroll") for (int k = 0; k < 2; ++k) dst[m][k] = *(const PG8_LAS bf16x8*)(lds + PG8_SA(b, h) + aoff + m * 2048 + k * 1024); } while (0)
; #define PG8_MMA(ai, bj, At, Bt) do { __builtin_amdgcn_s_setprio(1); _Pragma("unroll") for (int m = 0; m < 4; ++m) _Pragma("unroll") for (int n = 0; n < 2; ++n) _Pragma("unroll") for (int k = 0; k < 2; ++k) \
;         acc[ai][bj][m][n] = __builtin_amdgcn_mfma_f32_16x16x32_bf16(Bt[n][k], At[m][k], acc[ai][bj][m][n], 0, 0, 0); __builtin_amdgcn_s_setprio(0); } while (0)
; #define PG8_WAIT_V(n) asm volatile("s_waitcnt vmcnt(" #n ")" ::: "memory")
; #define PG8_WAIT_L(n) asm volatile("s_waitcnt lgkmcnt(" #n ")" ::: "memory")
; #define PG8_BAR __builtin_amdgcn_s_barrier()
; #define PG8_SCHED __builtin_amdgcn_sched_barrier(0)
; template <class Epi, class Sched, bool ALIGN_EPI = false, bool SP2 = false>
; __device__ __forceinline__ void gemm_phase(PG8_LAS unsigned char* lds, const Gemm g, const Sched& S, const Epi& E, int wv) {
;     ...
;         for (int t = 0; t < nt; t += 2) {
;             const bool last = (t == nt - 2);
;     ...
;             PG8_LDA(At, 1, 1); PG8_STAGE(PG8_SB(1, 0), b3, voffB); PG8_STAGE(PG8_SB(1, 1), b3 + hstepB, voffB); PG8_STAGE(PG8_SA(1, 0), a3, voffA);
;             PG8_WAIT_V(8); PG8_WAIT_L(0); PG8_BAR; PG8_MMA(1, 0, At, B0); PG8_MMA(1, 1, At, B1); PG8_BAR; PG8_SCHED;
	s_add_i32 s18, s96, s33
	v_lshl_add_u64 v[142:143], v[142:143], 0, s[20:21]
	s_mov_b32 m0, s18
	ds_read_b128 v[182:185], v146 offset:49152
	ds_read_b128 v[186:189], v146 offset:50176
	ds_read_b128 v[190:193], v146 offset:51200
	ds_read_b128 v[198:201], v146 offset:52224
	ds_read_b128 v[218:221], v146 offset:53248
	ds_read_b128 v[222:225], v146 offset:54272
	ds_read_b128 v[226:229], v146 offset:55296
	ds_read_b128 v[230:233], v146 offset:56320
	global_load_lds_dwordx4 v[142:143], off
	s_add_i32 m0, s18, 0x2000
	s_add_u32 s16, s16, 0x40080
	v_lshl_add_u64 v[142:143], v[194:195], 0, s[20:21]
	s_addc_u32 s17, s17, 0
	s_add_i32 s18, s97, s33
	global_load_lds_dwordx4 v[142:143], off
	v_lshl_add_u64 v[142:143], s[16:17], 0, v[132:133]
	s_mov_b32 m0, s18
	s_nop 0
	global_load_lds_dwordx4 v[142:143], off
	v_lshl_add_u64 v[142:143], s[16:17], 0, v[136:137]
	s_add_i32 m0, s18, 0x2000
	s_nop 0
	global_load_lds_dwordx4 v[142:143], off
	v_lshl_add_u64 v[142:143], v[196:197], 0, s[20:21]
	s_mov_b32 m0, s67
	s_nop 0
	global_load_lds_dwordx4 v[142:143], off
	v_lshl_add_u64 v[142:143], v[202:203], 0, s[20:21]
	s_mov_b32 m0, s69
	s_nop 0
	global_load_lds_dwordx4 v[142:143], off
	s_waitcnt vmcnt(8) lgkmcnt(0)
	s_barrier
	s_setprio 1
	v_mfma_f32_16x16x32_bf16 v[62:65], v[148:151], v[182:185], v[62:65]
	v_mfma_f32_16x16x32_bf16 v[58:61], v[158:161], v[182:185], v[58:61]
	v_mfma_f32_16x16x32_bf16 v[46:49], v[148:151], v[190:193], v[46:49]
	v_mfma_f32_16x16x32_bf16 v[42:45], v[158:161], v[190:193], v[42:45]
	v_mfma_f32_16x16x32_bf16 v[30:33], v[148:151], v[218:221], v[30:33]
	v_mfma_f32_16x16x32_bf16 v[26:29], v[158:161], v[218:221], v[26:29]
	v_mfma_f32_16x16x32_bf16 v[14:17], v[148:151], v[226:229], v[14:17]
	v_mfma_f32_16x16x32_bf16 v[10:13], v[158:161], v[226:229], v[10:13]
	v_mfma_f32_16x16x32_bf16 v[62:65], v[152:155], v[186:189], v[62:65]
	v_mfma_f32_16x16x32_bf16 v[58:61], v[162:165], v[186:189], v[58:61]
	v_mfma_f32_16x16x32_bf16 v[46:49], v[152:155], v[198:201], v[46:49]
	v_mfma_f32_16x16x32_bf16 v[42:45], v[162:165], v[198:201], v[42:45]
	v_mfma_f32_16x16x32_bf16 v[30:33], v[152:155], v[222:225], v[30:33]
	v_mfma_f32_16x16x32_bf16 v[26:29], v[162:165], v[222:225], v[26:29]
	v_mfma_f32_16x16x32_bf16 v[14:17], v[152:155], v[230:233], v[14:17]
	v_mfma_f32_16x16x32_bf16 v[10:13], v[162:165], v[230:233], v[10:13]
	v_mfma_f32_16x16x32_bf16 v[54:57], v[166:169], v[182:185], v[54:57]
	v_mfma_f32_16x16x32_bf16 v[50:53], v[174:177], v[182:185], v[50:53]
	v_mfma_f32_16x16x32_bf16 v[38:41], v[166:169], v[190:193], v[38:41]
	v_mfma_f32_16x16x32_bf16 v[34:37], v[174:177], v[190:193], v[34:37]
	v_mfma_f32_16x16x32_bf16 v[22:25], v[166:169], v[218:221], v[22:25]
	v_mfma_f32_16x16x32_bf16 v[18:21], v[174:177], v[218:221], v[18:21]
	v_mfma_f32_16x16x32_bf16 v[6:9], v[166:169], v[226:229], v[6:9]
	v_mfma_f32_16x16x32_bf16 v[2:5], v[174:177], v[226:229], v[2:5]
	v_mfma_f32_16x16x32_bf16 v[54:57], v[170:173], v[186:189], v[54:57]
	v_mfma_f32_16x16x32_bf16 v[50:53], v[178:181], v[186:189], v[50:53]
	v_mfma_f32_16x16x32_bf16 v[38:41], v[170:173], v[198:201], v[38:41]
	v_mfma_f32_16x16x32_bf16 v[34:37], v[178:181], v[198:201], v[34:37]
	v_mfma_f32_16x16x32_bf16 v[22:25], v[170:173], v[222:225], v[22:25]
	v_mfma_f32_16x16x32_bf16 v[18:21], v[178:181], v[222:225], v[18:21]
	v_mfma_f32_16x16x32_bf16 v[6:9], v[170:173], v[230:233], v[6:9]
	v_mfma_f32_16x16x32_bf16 v[2:5], v[178:181], v[230:233], v[2:5]
	s_setprio 0
	s_barrier
	s_add_i32 s79, s79, 2
	s_add_u32 s14, s14, 0x100
	s_addc_u32 s15, s15, 0
	s_add_u32 s76, s76, 0x100
	s_addc_u32 s77, s77, 0
	s_cmp_gt_u32 s79, 13
	s_cbranch_scc0 .LBB0_86
	s_and_b64 vcc, exec, s[2:3]
	s_cbranch_vccz .LBB0_89
	s_barrier

; #define PG8_STAGE(bufoff, gbase, voff) do { _Pragma("unroll") for (int _i = 0; _i < 2; ++_i) \
;         __builtin_amdgcn_global_load_lds((const unsigned*)((const char*)(gbase) + (voff)[_i]), (PG8_LAS unsigned*)(lds + (bufoff) + ldsw + _i * 8192), 16, 0, 0); } while (0)
; #define PG8_LDA(dst, b, h) do { _Pragma("unroll") for (int m = 0; m < 4; ++m) _Pragma("unroll") for (int k = 0; k < 2; ++k) dst[m][k] = *(const PG8_LAS bf16x8*)(lds + PG8_SA(b, h) + aoff + m * 2048 + k * 1024); } while (0)
; #define PG8_LDB(dst, b, h) do { _Pragma("unroll") for (int n = 0; n < 2; ++n) _Pragma("unroll") for (int k = 0; k < 2; ++k) dst[n][k] = *(const PG8_LAS bf16x8*)(lds + PG8_SB(b, h) + boff + n * 2048 + k * 1024); } while (0)
; #define PG8_MMA(ai, bj, At, Bt) do { __builtin_amdgcn_s_setprio(1); _Pragma("unroll") for (int m = 0; m < 4; ++m) _Pragma("unroll") for (int n = 0; n < 2; ++n) _Pragma("unroll") for (int k = 0; k < 2; ++k) \
;         acc[ai][bj][m][n] = __builtin_amdgcn_mfma_f32_16x16x32_bf16(Bt[n][k], At[m][k], acc[ai][bj][m][n], 0, 0, 0); __builtin_amdgcn_s_setprio(0); } while (0)
; #define PG8_WAIT_V(n) asm volatile("s_waitcnt vmcnt(" #n ")" ::: "memory")
; #define PG8_WAIT_L(n) asm volatile("s_waitcnt lgkmcnt(" #n ")" ::: "memory")
; #define PG8_BAR __builtin_amdgcn_s_barrier()
; #define PG8_SCHED __builtin_amdgcn_sched_barrier(0)
; template <class Epi, class Sched, bool ALIGN_EPI = false, bool SP2 = false>
; __device__ __forceinline__ void gemm_phase(PG8_LAS unsigned char* lds, const Gemm g, const Sched& S, const Epi& E, int wv) {
;     ...
;             const bool last = (t == nt - 2);
;             const char* a1 = cA + (size_t)(t + 1) * kstep;
;             const char* a2 = last ? nA : cA + (size_t)(t + 2) * kstep; const char* b2 = last ? nB : cB + (size_t)(t + 2) * kstep;
;             const char* a3 = a2 + kstep; const char* b3 = b2 + kstep;
;             if (last && has_next) S.a_ready(nxt);
;             if constexpr (SP2) {
;             PG8_LDB(B0, 0, 0); PG8_LDB(B1, 0, 1); PG8_SCHED; PG8_LDA(At, 0, 0); PG8_STAGE(PG8_SA(1, 1), a1 + hstepA, voffA);
;             PG8_WAIT_V(8); PG8_WAIT_L(0); PG8_BAR; PG8_MMA(0, 0, At, B0); PG8_MMA(0, 1, At, B1); PG8_BAR; PG8_SCHED;
;             PG8_LDA(At, 0, 1); PG8_STAGE(PG8_SB(0, 0), b2, voffB); PG8_STAGE(PG8_SB(0, 1), b2 + hstepB, voffB); PG8_STAGE(PG8_SA(0, 0), a2, voffA);
.LBB0_120:
	s_add_u32 s16, s14, 0xfffc0080
	s_addc_u32 s17, s15, -1
	s_add_i32 s96, 0, 0x10000
	s_cmp_eq_u32 s79, 12
	s_cselect_b32 s19, s7, s17
	s_cselect_b32 s18, s74, s16
	v_add_u32_e32 v142, s96, v145
	s_cselect_b32 s17, s5, s77
	s_cselect_b32 s16, s75, s76
	s_add_i32 vcc_lo, 0, 0x14000
	ds_read_b128 v[158:161], v142
	ds_read_b128 v[162:165], v142 offset:1024
	ds_read_b128 v[166:169], v142 offset:2048
	ds_read_b128 v[170:173], v142 offset:3072
	v_add_u32_e32 v142, vcc_lo, v145
	ds_read_b128 v[174:177], v142
	ds_read_b128 v[178:181], v142 offset:1024
	ds_read_b128 v[182:185], v142 offset:2048
	ds_read_b128 v[186:189], v142 offset:3072
	v_lshl_add_u64 v[142:143], s[14:15], 0, v[138:139]
	s_add_i32 m0, s40, 0xc000
	ds_read_b128 v[190:193], v153
	ds_read_b128 v[198:201], v153 offset:1024
	ds_read_b128 v[218:221], v153 offset:2048
	ds_read_b128 v[222:225], v153 offset:3072
	ds_read_b128 v[226:229], v153 offset:4096
	ds_read_b128 v[230:233], v153 offset:5120
	ds_read_b128 v[234:237], v153 offset:6144
	ds_read_b128 v[238:241], v153 offset:7168
	global_load_lds_dwordx4 v[142:143], off
	v_lshl_add_u64 v[142:143], s[14:15], 0, v[140:141]
	s_add_i32 m0, s40, 0xe000
	s_nop 0
	global_load_lds_dwordx4 v[142:143], off
	s_waitcnt vmcnt(8) lgkmcnt(0)
	s_barrier
	s_setprio 1
	v_mfma_f32_16x16x32_bf16 v[126:129], v[158:161], v[190:193], v[126:129]
	v_mfma_f32_16x16x32_bf16 v[122:125], v[166:169], v[190:193], v[122:125]
	v_mfma_f32_16x16x32_bf16 v[118:121], v[158:161], v[218:221], v[118:121]
	v_mfma_f32_16x16x32_bf16 v[110:113], v[166:169], v[218:221], v[110:113]
	v_mfma_f32_16x16x32_bf16 v[102:105], v[158:161], v[226:229], v[102:105]
	v_mfma_f32_16x16x32_bf16 v[94:97], v[166:169], v[226:229], v[94:97]
	v_mfma_f32_16x16x32_bf16 v[86:89], v[158:161], v[234:237], v[86:89]
	v_mfma_f32_16x16x32_bf16 v[78:81], v[166:169], v[234:237], v[78:81]
	v_mfma_f32_16x16x32_bf16 v[126:129], v[162:165], v[198:201], v[126:129]
	v_mfma_f32_16x16x32_bf16 v[122:125], v[170:173], v[198:201], v[122:125]
	v_mfma_f32_16x16x32_bf16 v[118:121], v[162:165], v[222:225], v[118:121]
	v_mfma_f32_16x16x32_bf16 v[110:113], v[170:173], v[222:225], v[110:113]
	v_mfma_f32_16x16x32_bf16 v[102:105], v[162:165], v[230:233], v[102:105]
	v_mfma_f32_16x16x32_bf16 v[94:97], v[170:173], v[230:233], v[94:97]
	v_mfma_f32_16x16x32_bf16 v[86:89], v[162:165], v[238:241], v[86:89]
	v_mfma_f32_16x16x32_bf16 v[78:81], v[170:173], v[238:241], v[78:81]
	v_mfma_f32_16x16x32_bf16 v[114:117], v[174:177], v[190:193], v[114:117]
	v_mfma_f32_16x16x32_bf16 v[106:109], v[182:185], v[190:193], v[106:109]
	v_mfma_f32_16x16x32_bf16 v[98:101], v[174:177], v[218:221], v[98:101]
	v_mfma_f32_16x16x32_bf16 v[90:93], v[182:185], v[218:221], v[90:93]
	v_mfma_f32_16x16x32_bf16 v[82:85], v[174:177], v[226:229], v[82:85]
	v_mfma_f32_16x16x32_bf16 v[74:77], v[182:185], v[226:229], v[74:77]
	v_mfma_f32_16x16x32_bf16 v[70:73], v[174:177], v[234:237], v[70:73]
	v_mfma_f32_16x16x32_bf16 v[66:69], v[182:185], v[234:237], v[66:69]
	v_mfma_f32_16x16x32_bf16 v[114:117], v[178:181], v[198:201], v[114:117]
	v_mfma_f32_16x16x32_bf16 v[106:109], v[186:189], v[198:201], v[106:109]
	v_mfma_f32_16x16x32_bf16 v[98:101], v[178:181], v[222:225], v[98:101]
	v_mfma_f32_16x16x32_bf16 v[90:93], v[186:189], v[222:225], v[90:93]
	v_mfma_f32_16x16x32_bf16 v[82:85], v[178:181], v[230:233], v[82:85]
	v_mfma_f32_16x16x32_bf16 v[74:77], v[186:189], v[230:233], v[74:77]
	v_mfma_f32_16x16x32_bf16 v[70:73], v[178:181], v[238:241], v[70:73]
	v_mfma_f32_16x16x32_bf16 v[66:69], v[186:189], v[238:241], v[66:69]
	s_setprio 0
	s_barrier
	s_add_i32 s96, s96, s33
	v_lshl_add_u64 v[142:143], s[16:17], 0, v[132:133]
	s_mov_b32 m0, s96
	ds_read_b128 v[190:193], v153 offset:16384
	ds_read_b128 v[198:201], v153 offset:17408
	ds_read_b128 v[218:221], v153 offset:18432
	ds_read_b128 v[222:225], v153 offset:19456
	ds_read_b128 v[226:229], v153 offset:20480
	ds_read_b128 v[230:233], v153 offset:21504
	ds_read_b128 v[234:237], v153 offset:22528
	ds_read_b128 v[238:241], v153 offset:23552
	global_load_lds_dwordx4 v[142:143], off
	s_add_i32 m0, s96, 0x2000
	s_add_u32 s96, s16, 0x40000
	v_lshl_add_u64 v[154:155], s[16:17], 0, v[136:137]
	s_addc_u32 s97, s17, 0
	s_add_i32 vcc_lo, vcc_lo, s33
	global_load_lds_dwordx4 v[154:155], off
	v_lshl_add_u64 v[194:195], s[96:97], 0, v[132:133]
	s_mov_b32 m0, vcc_lo
	v_lshl_add_u64 v[196:197], s[18:19], 0, v[134:135]
	global_load_lds_dwordx4 v[194:195], off
	v_lshl_add_u64 v[194:195], s[96:97], 0, v[136:137]
	s_add_i32 m0, vcc_lo, 0x2000
	s_nop 0
	global_load_lds_dwordx4 v[194:195], off
	v_lshl_add_u64 v[194:195], s[18:19], 0, v[130:131]
	s_mov_b32 m0, s40
	s_nop 0
	global_load_lds_dwordx4 v[194:195], off
	s_mov_b32 m0, s41
	s_nop 0
	global_load_lds_dwordx4 v[196:197], off
	s_waitcnt vmcnt(8) lgkmcnt(0)
	s_barrier
; #define PG8_STAGE(bufoff, gbase, voff) do { _Pragma("unroll") for (int _i = 0; _i < 2; ++_i) \
;         __builtin_amdgcn_global_load_lds((const unsigned*)((const char*)(gbase) + (voff)[_i]), (PG8_LAS unsigned*)(lds + (bufoff) + ldsw + _i * 8192), 16, 0, 0); } while (0)
; #define PG8_LDA(dst, b, h) do { _Pragma("unroll") for (int m = 0; m < 4; ++m) _Pragma("unroll") for (int k = 0; k < 2; ++k) dst[m][k] = *(const PG8_LAS bf16x8*)(lds + PG8_SA(b, h) + aoff + m * 2048 + k * 1024); } while (0)
; #define PG8_LDB(dst, b, h) do { _Pragma("unroll") for (int n = 0; n < 2; ++n) _Pragma("unroll") for (int k = 0; k < 2; ++k) dst[n][k] = *(const PG8_LAS bf16x8*)(lds + PG8_SB(b, h) + boff + n * 2048 + k * 1024); } while (0)
; #define PG8_MMA(ai, bj, At, Bt) do { __builtin_amdgcn_s_setprio(1); _Pragma("unroll") for (int m = 0; m < 4; ++m) _Pragma("unroll") for (int n = 0; n < 2; ++n) _Pragma("unroll") for (int k = 0; k < 2; ++k) \
;         acc[ai][bj][m][n] = __builtin_amdgcn_mfma_f32_16x16x32_bf16(Bt[n][k], At[m][k], acc[ai][bj][m][n], 0, 0, 0); __builtin_amdgcn_s_setprio(0); } while (0)
; #define PG8_WAIT_V(n) asm volatile("s_waitcnt vmcnt(" #n ")" ::: "memory")
; #define PG8_WAIT_L(n) asm volatile("s_waitcnt lgkmcnt(" #n ")" ::: "memory")
; #define PG8_BAR __builtin_amdgcn_s_barrier()
; #define PG8_SCHED __builtin_amdgcn_sched_barrier(0)
; template <class Epi, class Sched, bool ALIGN_EPI = false, bool SP2 = false>
; __device__ __forceinline__ void gemm_phase(PG8_LAS unsigned char* lds, const Gemm g, const Sched& S, const Epi& E, int wv) {
;     ...
;             PG8_WAIT_V(8); PG8_WAIT_L(0); PG8_BAR; PG8_MMA(1, 0, At, B0); PG8_MMA(1, 1, At, B1); PG8_BAR; PG8_SCHED;
;             PG8_LDB(B0, 1, 0); PG8_LDB(B1, 1, 1); PG8_SCHED; PG8_LDA(At, 1, 0); PG8_STAGE(PG8_SA(0, 1), a2 + hstepA, voffA);
;             PG8_WAIT_V(8); PG8_WAIT_L(0); PG8_BAR; PG8_MMA(0, 0, At, B0); PG8_MMA(0, 1, At, B1); PG8_BAR; PG8_SCHED;
	s_setprio 1
	v_mfma_f32_16x16x32_bf16 v[62:65], v[158:161], v[190:193], v[62:65]
	v_mfma_f32_16x16x32_bf16 v[58:61], v[166:169], v[190:193], v[58:61]
	v_mfma_f32_16x16x32_bf16 v[54:57], v[158:161], v[218:221], v[54:57]
	v_mfma_f32_16x16x32_bf16 v[46:49], v[166:169], v[218:221], v[46:49]
	v_mfma_f32_16x16x32_bf16 v[38:41], v[158:161], v[226:229], v[38:41]
	v_mfma_f32_16x16x32_bf16 v[30:33], v[166:169], v[226:229], v[30:33]
	v_mfma_f32_16x16x32_bf16 v[22:25], v[158:161], v[234:237], v[22:25]
	v_mfma_f32_16x16x32_bf16 v[14:17], v[166:169], v[234:237], v[14:17]
	v_mfma_f32_16x16x32_bf16 v[62:65], v[162:165], v[198:201], v[62:65]
	v_mfma_f32_16x16x32_bf16 v[58:61], v[170:173], v[198:201], v[58:61]
	v_mfma_f32_16x16x32_bf16 v[54:57], v[162:165], v[222:225], v[54:57]
	v_mfma_f32_16x16x32_bf16 v[46:49], v[170:173], v[222:225], v[46:49]
	v_mfma_f32_16x16x32_bf16 v[38:41], v[162:165], v[230:233], v[38:41]
	v_mfma_f32_16x16x32_bf16 v[30:33], v[170:173], v[230:233], v[30:33]
	v_mfma_f32_16x16x32_bf16 v[22:25], v[162:165], v[238:241], v[22:25]
	v_mfma_f32_16x16x32_bf16 v[14:17], v[170:173], v[238:241], v[14:17]
	v_mfma_f32_16x16x32_bf16 v[50:53], v[174:177], v[190:193], v[50:53]
	v_mfma_f32_16x16x32_bf16 v[42:45], v[182:185], v[190:193], v[42:45]
	v_mfma_f32_16x16x32_bf16 v[34:37], v[174:177], v[218:221], v[34:37]
	v_mfma_f32_16x16x32_bf16 v[26:29], v[182:185], v[218:221], v[26:29]
	v_mfma_f32_16x16x32_bf16 v[18:21], v[174:177], v[226:229], v[18:21]
	v_mfma_f32_16x16x32_bf16 v[10:13], v[182:185], v[226:229], v[10:13]
	v_mfma_f32_16x16x32_bf16 v[6:9], v[174:177], v[234:237], v[6:9]
	v_mfma_f32_16x16x32_bf16 v[2:5], v[182:185], v[234:237], v[2:5]
	v_mfma_f32_16x16x32_bf16 v[50:53], v[178:181], v[198:201], v[50:53]
	v_mfma_f32_16x16x32_bf16 v[42:45], v[186:189], v[198:201], v[42:45]
	v_mfma_f32_16x16x32_bf16 v[34:37], v[178:181], v[222:225], v[34:37]
	v_mfma_f32_16x16x32_bf16 v[26:29], v[186:189], v[222:225], v[26:29]
	v_mfma_f32_16x16x32_bf16 v[18:21], v[178:181], v[230:233], v[18:21]
	v_mfma_f32_16x16x32_bf16 v[10:13], v[186:189], v[230:233], v[10:13]
	v_mfma_f32_16x16x32_bf16 v[6:9], v[178:181], v[238:241], v[6:9]
	v_mfma_f32_16x16x32_bf16 v[2:5], v[186:189], v[238:241], v[2:5]
	s_setprio 0
	s_barrier
	s_add_i32 s96, 0, 0x18000
	v_add_u32_e32 v157, s96, v145
	s_add_i32 s97, 0, 0x1c000
	ds_read_b128 v[158:161], v157
	ds_read_b128 v[162:165], v157 offset:1024
	ds_read_b128 v[166:169], v157 offset:2048
	ds_read_b128 v[170:173], v157 offset:3072
	v_add_u32_e32 v157, s97, v145
	ds_read_b128 v[174:177], v157
	ds_read_b128 v[178:181], v157 offset:1024
	ds_read_b128 v[182:185], v157 offset:2048
	ds_read_b128 v[186:189], v157 offset:3072
	s_add_u32 s18, s18, 0x40000
	s_addc_u32 s19, s19, 0
	s_mov_b32 m0, s42
	v_lshl_add_u64 v[202:203], s[18:19], 0, v[130:131]
	ds_read_b128 v[190:193], v153 offset:32768
	ds_read_b128 v[198:201], v153 offset:33792
	ds_read_b128 v[218:221], v153 offset:34816
	ds_read_b128 v[222:225], v153 offset:35840
	ds_read_b128 v[226:229], v153 offset:36864
	ds_read_b128 v[230:233], v153 offset:37888
	ds_read_b128 v[234:237], v153 offset:38912
	ds_read_b128 v[238:241], v153 offset:39936
	global_load_lds_dwordx4 v[202:203], off
	v_lshl_add_u64 v[202:203], s[18:19], 0, v[134:135]
	s_mov_b32 m0, s43
	s_nop 0
	global_load_lds_dwordx4 v[202:203], off
	s_waitcnt vmcnt(8) lgkmcnt(0)
	s_barrier
	s_setprio 1
	v_mfma_f32_16x16x32_bf16 v[126:129], v[158:161], v[190:193], v[126:129]
	v_mfma_f32_16x16x32_bf16 v[122:125], v[166:169], v[190:193], v[122:125]
	v_mfma_f32_16x16x32_bf16 v[118:121], v[158:161], v[218:221], v[118:121]
	v_mfma_f32_16x16x32_bf16 v[110:113], v[166:169], v[218:221], v[110:113]
	v_mfma_f32_16x16x32_bf16 v[102:105], v[158:161], v[226:229], v[102:105]
	v_mfma_f32_16x16x32_bf16 v[94:97], v[166:169], v[226:229], v[94:97]
	v_mfma_f32_16x16x32_bf16 v[86:89], v[158:161], v[234:237], v[86:89]
	v_mfma_f32_16x16x32_bf16 v[78:81], v[166:169], v[234:237], v[78:81]
	v_mfma_f32_16x16x32_bf16 v[126:129], v[162:165], v[198:201], v[126:129]
	v_mfma_f32_16x16x32_bf16 v[122:125], v[170:173], v[198:201], v[122:125]
	v_mfma_f32_16x16x32_bf16 v[118:121], v[162:165], v[222:225], v[118:121]
	v_mfma_f32_16x16x32_bf16 v[110:113], v[170:173], v[222:225], v[110:113]
	v_mfma_f32_16x16x32_bf16 v[102:105], v[162:165], v[230:233], v[102:105]
	v_mfma_f32_16x16x32_bf16 v[94:97], v[170:173], v[230:233], v[94:97]
	v_mfma_f32_16x16x32_bf16 v[86:89], v[162:165], v[238:241], v[86:89]
	v_mfma_f32_16x16x32_bf16 v[78:81], v[170:173], v[238:241], v[78:81]
	v_mfma_f32_16x16x32_bf16 v[114:117], v[174:177], v[190:193], v[114:117]
	v_mfma_f32_16x16x32_bf16 v[106:109], v[182:185], v[190:193], v[106:109]
	v_mfma_f32_16x16x32_bf16 v[98:101], v[174:177], v[218:221], v[98:101]
	v_mfma_f32_16x16x32_bf16 v[90:93], v[182:185], v[218:221], v[90:93]
	v_mfma_f32_16x16x32_bf16 v[82:85], v[174:177], v[226:229], v[82:85]
	v_mfma_f32_16x16x32_bf16 v[74:77], v[182:185], v[226:229], v[74:77]
	v_mfma_f32_16x16x32_bf16 v[70:73], v[174:177], v[234:237], v[70:73]
	v_mfma_f32_16x16x32_bf16 v[66:69], v[182:185], v[234:237], v[66:69]
	v_mfma_f32_16x16x32_bf16 v[114:117], v[178:181], v[198:201], v[114:117]
	v_mfma_f32_16x16x32_bf16 v[106:109], v[186:189], v[198:201], v[106:109]
	v_mfma_f32_16x16x32_bf16 v[98:101], v[178:181], v[222:225], v[98:101]
	v_mfma_f32_16x16x32_bf16 v[90:93], v[186:189], v[222:225], v[90:93]
	v_mfma_f32_16x16x32_bf16 v[82:85], v[178:181], v[230:233], v[82:85]
	v_mfma_f32_16x16x32_bf16 v[74:77], v[186:189], v[230:233], v[74:77]
	v_mfma_f32_16x16x32_bf16 v[70:73], v[178:181], v[238:241], v[70:73]
	v_mfma_f32_16x16x32_bf16 v[66:69], v[186:189], v[238:241], v[66:69]
	s_setprio 0
	s_barrier
; #define PG8_STAGE(bufoff, gbase, voff) do { _Pragma("unroll") for (int _i = 0; _i < 2; ++_i) \
;         __builtin_amdgcn_global_load_lds((const unsigned*)((const char*)(gbase) + (voff)[_i]), (PG8_LAS unsigned*)(lds + (bufoff) + ldsw + _i * 8192), 16, 0, 0); } while (0)
; #define PG8_LDA(dst, b, h) do { _Pragma("unroll") for (int m = 0; m < 4; ++m) _Pragma("unroll") for (int k = 0; k < 2; ++k) dst[m][k] = *(const PG8_LAS bf16x8*)(lds + PG8_SA(b, h) + aoff + m * 2048 + k * 1024); } while (0)
; #define PG8_MMA(ai, bj, At, Bt) do { __builtin_amdgcn_s_setprio(1); _Pragma("unroll") for (int m = 0; m < 4; ++m) _Pragma("unroll") for (int n = 0; n < 2; ++n) _Pragma("unroll") for (int k = 0; k < 2; ++k) \
;         acc[ai][bj][m][n] = __builtin_amdgcn_mfma_f32_16x16x32_bf16(Bt[n][k], At[m][k], acc[ai][bj][m][n], 0, 0, 0); __builtin_amdgcn_s_setprio(0); } while (0)
; #define PG8_WAIT_V(n) asm volatile("s_waitcnt vmcnt(" #n ")" ::: "memory")
; #define PG8_WAIT_L(n) asm volatile("s_waitcnt lgkmcnt(" #n ")" ::: "memory")
; #define PG8_BAR __builtin_amdgcn_s_barrier()
; #define PG8_SCHED __builtin_amdgcn_sched_barrier(0)
; template <class Epi, class Sched, bool ALIGN_EPI = false, bool SP2 = false>
; __device__ __forceinline__ void gemm_phase(PG8_LAS unsigned char* lds, const Gemm g, const Sched& S, const Epi& E, int wv) {
;     ...
;         for (int t = 0; t < nt; t += 2) {
;             const bool last = (t == nt - 2);
;     ...
;             PG8_LDA(At, 1, 1); PG8_STAGE(PG8_SB(1, 0), b3, voffB); PG8_STAGE(PG8_SB(1, 1), b3 + hstepB, voffB); PG8_STAGE(PG8_SA(1, 0), a3, voffA);
;             PG8_WAIT_V(8); PG8_WAIT_L(0); PG8_BAR; PG8_MMA(1, 0, At, B0); PG8_MMA(1, 1, At, B1); PG8_BAR; PG8_SCHED;
	s_add_i32 s18, s96, s33
	v_lshl_add_u64 v[142:143], v[142:143], 0, s[20:21]
	s_mov_b32 m0, s18
	ds_read_b128 v[190:193], v153 offset:49152
	ds_read_b128 v[198:201], v153 offset:50176
	ds_read_b128 v[218:221], v153 offset:51200
	ds_read_b128 v[222:225], v153 offset:52224
	ds_read_b128 v[226:229], v153 offset:53248
	ds_read_b128 v[230:233], v153 offset:54272
	ds_read_b128 v[234:237], v153 offset:55296
	ds_read_b128 v[238:241], v153 offset:56320
	global_load_lds_dwordx4 v[142:143], off
	s_add_i32 m0, s18, 0x2000
	s_add_u32 s16, s16, 0x40080
	v_lshl_add_u64 v[142:143], v[154:155], 0, s[20:21]
	s_addc_u32 s17, s17, 0
	s_add_i32 s18, s97, s33
	global_load_lds_dwordx4 v[142:143], off
	v_lshl_add_u64 v[142:143], s[16:17], 0, v[132:133]
	s_mov_b32 m0, s18
	s_nop 0
	global_load_lds_dwordx4 v[142:143], off
	v_lshl_add_u64 v[142:143], s[16:17], 0, v[136:137]
	s_add_i32 m0, s18, 0x2000
	s_nop 0
	global_load_lds_dwordx4 v[142:143], off
	v_lshl_add_u64 v[142:143], v[194:195], 0, s[20:21]
	s_mov_b32 m0, s67
	s_nop 0
	global_load_lds_dwordx4 v[142:143], off
	v_lshl_add_u64 v[142:143], v[196:197], 0, s[20:21]
	s_mov_b32 m0, s69
	s_nop 0
	global_load_lds_dwordx4 v[142:143], off
	s_waitcnt vmcnt(8) lgkmcnt(0)
	s_barrier
	s_setprio 1
	v_mfma_f32_16x16x32_bf16 v[62:65], v[158:161], v[190:193], v[62:65]
	v_mfma_f32_16x16x32_bf16 v[58:61], v[166:169], v[190:193], v[58:61]
	v_mfma_f32_16x16x32_bf16 v[54:57], v[158:161], v[218:221], v[54:57]
	v_mfma_f32_16x16x32_bf16 v[46:49], v[166:169], v[218:221], v[46:49]
	v_mfma_f32_16x16x32_bf16 v[38:41], v[158:161], v[226:229], v[38:41]
	v_mfma_f32_16x16x32_bf16 v[30:33], v[166:169], v[226:229], v[30:33]
	v_mfma_f32_16x16x32_bf16 v[22:25], v[158:161], v[234:237], v[22:25]
	v_mfma_f32_16x16x32_bf16 v[14:17], v[166:169], v[234:237], v[14:17]
	v_mfma_f32_16x16x32_bf16 v[62:65], v[162:165], v[198:201], v[62:65]
	v_mfma_f32_16x16x32_bf16 v[58:61], v[170:173], v[198:201], v[58:61]
	v_mfma_f32_16x16x32_bf16 v[54:57], v[162:165], v[222:225], v[54:57]
	v_mfma_f32_16x16x32_bf16 v[46:49], v[170:173], v[222:225], v[46:49]
	v_mfma_f32_16x16x32_bf16 v[38:41], v[162:165], v[230:233], v[38:41]
	v_mfma_f32_16x16x32_bf16 v[30:33], v[170:173], v[230:233], v[30:33]
	v_mfma_f32_16x16x32_bf16 v[22:25], v[162:165], v[238:241], v[22:25]
	v_mfma_f32_16x16x32_bf16 v[14:17], v[170:173], v[238:241], v[14:17]
	v_mfma_f32_16x16x32_bf16 v[50:53], v[174:177], v[190:193], v[50:53]
	v_mfma_f32_16x16x32_bf16 v[42:45], v[182:185], v[190:193], v[42:45]
	v_mfma_f32_16x16x32_bf16 v[34:37], v[174:177], v[218:221], v[34:37]
	v_mfma_f32_16x16x32_bf16 v[26:29], v[182:185], v[218:221], v[26:29]
	v_mfma_f32_16x16x32_bf16 v[18:21], v[174:177], v[226:229], v[18:21]
	v_mfma_f32_16x16x32_bf16 v[10:13], v[182:185], v[226:229], v[10:13]
	v_mfma_f32_16x16x32_bf16 v[6:9], v[174:177], v[234:237], v[6:9]
	v_mfma_f32_16x16x32_bf16 v[2:5], v[182:185], v[234:237], v[2:5]
	v_mfma_f32_16x16x32_bf16 v[50:53], v[178:181], v[198:201], v[50:53]
	v_mfma_f32_16x16x32_bf16 v[42:45], v[186:189], v[198:201], v[42:45]
	v_mfma_f32_16x16x32_bf16 v[34:37], v[178:181], v[222:225], v[34:37]
	v_mfma_f32_16x16x32_bf16 v[26:29], v[186:189], v[222:225], v[26:29]
	v_mfma_f32_16x16x32_bf16 v[18:21], v[178:181], v[230:233], v[18:21]
	v_mfma_f32_16x16x32_bf16 v[10:13], v[186:189], v[230:233], v[10:13]
	v_mfma_f32_16x16x32_bf16 v[6:9], v[178:181], v[238:241], v[6:9]
	v_mfma_f32_16x16x32_bf16 v[2:5], v[186:189], v[238:241], v[2:5]
	s_setprio 0
	s_barrier
	s_add_i32 s79, s79, 2
	s_add_u32 s14, s14, 0x100
	s_addc_u32 s15, s15, 0
	s_add_u32 s76, s76, 0x100
	s_addc_u32 s77, s77, 0
	s_cmp_gt_u32 s79, 13
	s_cbranch_scc0 .LBB0_120
	s_and_b64 vcc, exec, s[2:3]
	s_cbranch_vccz .LBB0_123
	s_barrier

; #define PG8_STAGE(bufoff, gbase, voff) do { _Pragma("unroll") for (int _i = 0; _i < 2; ++_i) \
;         __builtin_amdgcn_global_load_lds((const unsigned*)((const char*)(gbase) + (voff)[_i]), (PG8_LAS unsigned*)(lds + (bufoff) + ldsw + _i * 8192), 16, 0, 0); } while (0)
; #define PG8_LDA(dst, b, h) do { _Pragma("unroll") for (int m = 0; m < 4; ++m) _Pragma("unroll") for (int k = 0; k < 2; ++k) dst[m][k] = *(const PG8_LAS bf16x8*)(lds + PG8_SA(b, h) + aoff + m * 2048 + k * 1024); } while (0)
; #define PG8_LDB(dst, b, h) do { _Pragma("unroll") for (int n = 0; n < 2; ++n) _Pragma("unroll") for (int k = 0; k < 2; ++k) dst[n][k] = *(const PG8_LAS bf16x8*)(lds + PG8_SB(b, h) + boff + n * 2048 + k * 1024); } while (0)
; #define PG8_MMA(ai, bj, At, Bt) do { __builtin_amdgcn_s_setprio(1); _Pragma("unroll") for (int m = 0; m < 4; ++m) _Pragma("unroll") for (int n = 0; n < 2; ++n) _Pragma("unroll") for (int k = 0; k < 2; ++k) \
;         acc[ai][bj][m][n] = __builtin_amdgcn_mfma_f32_16x16x32_bf16(Bt[n][k], At[m][k], acc[ai][bj][m][n], 0, 0, 0); __builtin_amdgcn_s_setprio(0); } while (0)
; template <class Epi, class Sched, bool ALIGN_EPI = false, bool SP2 = false>
; __device__ __forceinline__ void gemm_phase(PG8_LAS unsigned char* lds, const Gemm g, const Sched& S, const Epi& E, int wv) {
;     ...
;             if constexpr (SP2) {
;             PG8_LDB(B0, 0, 0); PG8_LDB(B1, 0, 1); PG8_SCHED; PG8_LDA(At, 0, 0); PG8_STAGE(PG8_SA(1, 1), a1 + hstepA, voffA);
;             PG8_WAIT_V(8); PG8_WAIT_L(0); PG8_BAR; PG8_MMA(0, 0, At, B0); PG8_MMA(0, 1, At, B1); PG8_BAR; PG8_SCHED;
;             PG8_LDA(At, 0, 1); PG8_STAGE(PG8_SB(0, 0), b2, voffB); PG8_STAGE(PG8_SB(0, 1), b2 + hstepB, voffB); PG8_STAGE(PG8_SA(0, 0), a2, voffA);
;             PG8_WAIT_V(8); PG8_WAIT_L(0); PG8_BAR; PG8_MMA(1, 0, At, B0); PG8_MMA(1, 1, At, B1); PG8_BAR; PG8_SCHED;
;             PG8_LDB(B0, 1, 0); PG8_LDB(B1, 1, 1); PG8_SCHED; PG8_LDA(At, 1, 0); PG8_STAGE(PG8_SA(0, 1), a2 + hstepA, voffA);
;             PG8_WAIT_V(8); PG8_WAIT_L(0); PG8_BAR; PG8_MMA(0, 0, At, B0); PG8_MMA(0, 1, At, B1); PG8_BAR; PG8_SCHED;
;             PG8_LDA(At, 1, 1); PG8_STAGE(PG8_SB(1, 0), b3, voffB); PG8_STAGE(PG8_SB(1, 1), b3 + hstepB, voffB); PG8_STAGE(PG8_SA(1, 0), a3, voffA);
;             PG8_WAIT_V(8); PG8_WAIT_L(0); PG8_BAR; PG8_MMA(1, 0, At, B0); PG8_MMA(1, 1, At, B1); PG8_BAR; PG8_SCHED;
.LBB0_140:
	s_add_u32 s6, s4, 0x100
	s_addc_u32 s7, s5, 0
	s_add_i32 s65, 0, 0x10000
	s_cmp_eq_u32 s37, 12
	s_cselect_b32 s11, s41, s7
	s_cselect_b32 s10, s40, s6
	v_add_u32_e32 v0, s65, v146
	s_cselect_b32 s9, s30, s36
	s_cselect_b32 s8, s31, s33
	s_add_i32 s69, 0, 0x14000
	ds_read_b128 v[142:145], v0
	ds_read_b128 v[166:169], v0 offset:1024
	ds_read_b128 v[170:173], v0 offset:2048
	ds_read_b128 v[174:177], v0 offset:3072
	v_add_u32_e32 v0, s69, v146
	ds_read_b128 v[178:181], v0
	ds_read_b128 v[182:185], v0 offset:1024
	ds_read_b128 v[186:189], v0 offset:2048
	ds_read_b128 v[190:193], v0 offset:3072
	v_lshl_add_u64 v[194:195], s[4:5], 0, v[138:139]
	s_add_i32 m0, s1, 0xc000
	ds_read_b128 v[198:201], v165
	ds_read_b128 v[218:221], v165 offset:1024
	ds_read_b128 v[222:225], v165 offset:2048
	ds_read_b128 v[226:229], v165 offset:3072
	ds_read_b128 v[230:233], v165 offset:4096
	ds_read_b128 v[234:237], v165 offset:5120
	ds_read_b128 v[238:241], v165 offset:6144
	ds_read_b128 v[242:245], v165 offset:7168
	global_load_lds_dwordx4 v[194:195], off
	v_lshl_add_u64 v[194:195], s[4:5], 0, v[140:141]
	s_add_i32 m0, s1, 0xe000
	s_nop 0
	global_load_lds_dwordx4 v[194:195], off
	s_waitcnt vmcnt(8) lgkmcnt(0)
	s_barrier
	s_setprio 1
	v_mfma_f32_16x16x32_bf16 v[126:129], v[142:145], v[198:201], v[126:129]
	v_mfma_f32_16x16x32_bf16 v[122:125], v[170:173], v[198:201], v[122:125]
	v_mfma_f32_16x16x32_bf16 v[110:113], v[142:145], v[222:225], v[110:113]
	v_mfma_f32_16x16x32_bf16 v[106:109], v[170:173], v[222:225], v[106:109]
	v_mfma_f32_16x16x32_bf16 v[94:97], v[142:145], v[230:233], v[94:97]
	v_mfma_f32_16x16x32_bf16 v[90:93], v[170:173], v[230:233], v[90:93]
	v_mfma_f32_16x16x32_bf16 v[78:81], v[142:145], v[238:241], v[78:81]
	v_mfma_f32_16x16x32_bf16 v[74:77], v[170:173], v[238:241], v[74:77]
	v_mfma_f32_16x16x32_bf16 v[126:129], v[166:169], v[218:221], v[126:129]
	v_mfma_f32_16x16x32_bf16 v[122:125], v[174:177], v[218:221], v[122:125]
	v_mfma_f32_16x16x32_bf16 v[110:113], v[166:169], v[226:229], v[110:113]
	v_mfma_f32_16x16x32_bf16 v[106:109], v[174:177], v[226:229], v[106:109]
	v_mfma_f32_16x16x32_bf16 v[94:97], v[166:169], v[234:237], v[94:97]
	v_mfma_f32_16x16x32_bf16 v[90:93], v[174:177], v[234:237], v[90:93]
	v_mfma_f32_16x16x32_bf16 v[78:81], v[166:169], v[242:245], v[78:81]
	v_mfma_f32_16x16x32_bf16 v[74:77], v[174:177], v[242:245], v[74:77]
	v_mfma_f32_16x16x32_bf16 v[118:121], v[178:181], v[198:201], v[118:121]
	v_mfma_f32_16x16x32_bf16 v[114:117], v[186:189], v[198:201], v[114:117]
	v_mfma_f32_16x16x32_bf16 v[102:105], v[178:181], v[222:225], v[102:105]
	v_mfma_f32_16x16x32_bf16 v[98:101], v[186:189], v[222:225], v[98:101]
	v_mfma_f32_16x16x32_bf16 v[86:89], v[178:181], v[230:233], v[86:89]
	v_mfma_f32_16x16x32_bf16 v[82:85], v[186:189], v[230:233], v[82:85]
	v_mfma_f32_16x16x32_bf16 v[70:73], v[178:181], v[238:241], v[70:73]
	v_mfma_f32_16x16x32_bf16 v[66:69], v[186:189], v[238:241], v[66:69]
	v_mfma_f32_16x16x32_bf16 v[118:121], v[182:185], v[218:221], v[118:121]
	v_mfma_f32_16x16x32_bf16 v[114:117], v[190:193], v[218:221], v[114:117]
	v_mfma_f32_16x16x32_bf16 v[102:105], v[182:185], v[226:229], v[102:105]
	v_mfma_f32_16x16x32_bf16 v[98:101], v[190:193], v[226:229], v[98:101]
	v_mfma_f32_16x16x32_bf16 v[86:89], v[182:185], v[234:237], v[86:89]
	v_mfma_f32_16x16x32_bf16 v[82:85], v[190:193], v[234:237], v[82:85]
	v_mfma_f32_16x16x32_bf16 v[70:73], v[182:185], v[242:245], v[70:73]
	v_mfma_f32_16x16x32_bf16 v[66:69], v[190:193], v[242:245], v[66:69]
	s_setprio 0
	s_barrier
	s_add_i32 s4, s65, s14
	v_lshl_add_u64 v[194:195], s[8:9], 0, v[132:133]
	s_mov_b32 m0, s4
	ds_read_b128 v[198:201], v165 offset:16384
	ds_read_b128 v[218:221], v165 offset:17408
	ds_read_b128 v[222:225], v165 offset:18432
	ds_read_b128 v[226:229], v165 offset:19456
	ds_read_b128 v[230:233], v165 offset:20480
	ds_read_b128 v[234:237], v165 offset:21504
	ds_read_b128 v[238:241], v165 offset:22528
	ds_read_b128 v[242:245], v165 offset:23552
	global_load_lds_dwordx4 v[194:195], off
	s_add_i32 m0, s4, 0x2000
	s_add_u32 s4, s8, 0x40000
	v_lshl_add_u64 v[196:197], s[8:9], 0, v[136:137]
	s_addc_u32 s5, s9, 0
	s_add_i32 s65, s69, s14
	global_load_lds_dwordx4 v[196:197], off
	v_lshl_add_u64 v[202:203], s[4:5], 0, v[132:133]
	s_mov_b32 m0, s65
	v_lshl_add_u64 v[204:205], s[10:11], 0, v[134:135]
	global_load_lds_dwordx4 v[202:203], off
	v_lshl_add_u64 v[202:203], s[4:5], 0, v[136:137]
	s_add_i32 m0, s65, 0x2000
	s_nop 0
	global_load_lds_dwordx4 v[202:203], off
	v_lshl_add_u64 v[202:203], s[10:11], 0, v[130:131]
	s_mov_b32 m0, s1
	s_nop 0
	global_load_lds_dwordx4 v[202:203], off
	s_mov_b32 m0, s17
	s_nop 0
	global_load_lds_dwordx4 v[204:205], off
	s_waitcnt vmcnt(8) lgkmcnt(0)
	s_barrier
; #define PG8_STAGE(bufoff, gbase, voff) do { _Pragma("unroll") for (int _i = 0; _i < 2; ++_i) \
;         __builtin_amdgcn_global_load_lds((const unsigned*)((const char*)(gbase) + (voff)[_i]), (PG8_LAS unsigned*)(lds + (bufoff) + ldsw + _i * 8192), 16, 0, 0); } while (0)
; #define PG8_LDA(dst, b, h) do { _Pragma("unroll") for (int m = 0; m < 4; ++m) _Pragma("unroll") for (int k = 0; k < 2; ++k) dst[m][k] = *(const PG8_LAS bf16x8*)(lds + PG8_SA(b, h) + aoff + m * 2048 + k * 1024); } while (0)
; #define PG8_LDB(dst, b, h) do { _Pragma("unroll") for (int n = 0; n < 2; ++n) _Pragma("unroll") for (int k = 0; k < 2; ++k) dst[n][k] = *(const PG8_LAS bf16x8*)(lds + PG8_SB(b, h) + boff + n * 2048 + k * 1024); } while (0)
; #define PG8_MMA(ai, bj, At, Bt) do { __builtin_amdgcn_s_setprio(1); _Pragma("unroll") for (int m = 0; m < 4; ++m) _Pragma("unroll") for (int n = 0; n < 2; ++n) _Pragma("unroll") for (int k = 0; k < 2; ++k) \
;         acc[ai][bj][m][n] = __builtin_amdgcn_mfma_f32_16x16x32_bf16(Bt[n][k], At[m][k], acc[ai][bj][m][n], 0, 0, 0); __builtin_amdgcn_s_setprio(0); } while (0)
; template <class Epi, class Sched, bool ALIGN_EPI = false, bool SP2 = false>
; __device__ __forceinline__ void gemm_phase(PG8_LAS unsigned char* lds, const Gemm g, const Sched& S, const Epi& E, int wv) {
;     ...
;             if constexpr (SP2) {
;             PG8_LDB(B0, 0, 0); PG8_LDB(B1, 0, 1); PG8_SCHED; PG8_LDA(At, 0, 0); PG8_STAGE(PG8_SA(1, 1), a1 + hstepA, voffA);
;             PG8_WAIT_V(8); PG8_WAIT_L(0); PG8_BAR; PG8_MMA(0, 0, At, B0); PG8_MMA(0, 1, At, B1); PG8_BAR; PG8_SCHED;
;             PG8_LDA(At, 0, 1); PG8_STAGE(PG8_SB(0, 0), b2, voffB); PG8_STAGE(PG8_SB(0, 1), b2 + hstepB, voffB); PG8_STAGE(PG8_SA(0, 0), a2, voffA);
;             PG8_WAIT_V(8); PG8_WAIT_L(0); PG8_BAR; PG8_MMA(1, 0, At, B0); PG8_MMA(1, 1, At, B1); PG8_BAR; PG8_SCHED;
;             PG8_LDB(B0, 1, 0); PG8_LDB(B1, 1, 1); PG8_SCHED; PG8_LDA(At, 1, 0); PG8_STAGE(PG8_SA(0, 1), a2 + hstepA, voffA);
;             PG8_WAIT_V(8); PG8_WAIT_L(0); PG8_BAR; PG8_MMA(0, 0, At, B0); PG8_MMA(0, 1, At, B1); PG8_BAR; PG8_SCHED;
;             PG8_LDA(At, 1, 1); PG8_STAGE(PG8_SB(1, 0), b3, voffB); PG8_STAGE(PG8_SB(1, 1), b3 + hstepB, voffB); PG8_STAGE(PG8_SA(1, 0), a3, voffA);
;             PG8_WAIT_V(8); PG8_WAIT_L(0); PG8_BAR; PG8_MMA(1, 0, At, B0); PG8_MMA(1, 1, At, B1); PG8_BAR; PG8_SCHED;
	s_setprio 1
	v_mfma_f32_16x16x32_bf16 v[62:65], v[142:145], v[198:201], v[62:65]
	v_mfma_f32_16x16x32_bf16 v[58:61], v[170:173], v[198:201], v[58:61]
	v_mfma_f32_16x16x32_bf16 v[46:49], v[142:145], v[222:225], v[46:49]
	v_mfma_f32_16x16x32_bf16 v[42:45], v[170:173], v[222:225], v[42:45]
	v_mfma_f32_16x16x32_bf16 v[30:33], v[142:145], v[230:233], v[30:33]
	v_mfma_f32_16x16x32_bf16 v[26:29], v[170:173], v[230:233], v[26:29]
	v_mfma_f32_16x16x32_bf16 v[14:17], v[142:145], v[238:241], v[14:17]
	v_mfma_f32_16x16x32_bf16 v[10:13], v[170:173], v[238:241], v[10:13]
	v_mfma_f32_16x16x32_bf16 v[62:65], v[166:169], v[218:221], v[62:65]
	v_mfma_f32_16x16x32_bf16 v[58:61], v[174:177], v[218:221], v[58:61]
	v_mfma_f32_16x16x32_bf16 v[46:49], v[166:169], v[226:229], v[46:49]
	v_mfma_f32_16x16x32_bf16 v[42:45], v[174:177], v[226:229], v[42:45]
	v_mfma_f32_16x16x32_bf16 v[30:33], v[166:169], v[234:237], v[30:33]
	v_mfma_f32_16x16x32_bf16 v[26:29], v[174:177], v[234:237], v[26:29]
	v_mfma_f32_16x16x32_bf16 v[14:17], v[166:169], v[242:245], v[14:17]
	v_mfma_f32_16x16x32_bf16 v[10:13], v[174:177], v[242:245], v[10:13]
	v_mfma_f32_16x16x32_bf16 v[54:57], v[178:181], v[198:201], v[54:57]
	v_mfma_f32_16x16x32_bf16 v[50:53], v[186:189], v[198:201], v[50:53]
	v_mfma_f32_16x16x32_bf16 v[38:41], v[178:181], v[222:225], v[38:41]
	v_mfma_f32_16x16x32_bf16 v[34:37], v[186:189], v[222:225], v[34:37]
	v_mfma_f32_16x16x32_bf16 v[22:25], v[178:181], v[230:233], v[22:25]
	v_mfma_f32_16x16x32_bf16 v[18:21], v[186:189], v[230:233], v[18:21]
	v_mfma_f32_16x16x32_bf16 v[6:9], v[178:181], v[238:241], v[6:9]
	v_mfma_f32_16x16x32_bf16 v[2:5], v[186:189], v[238:241], v[2:5]
	v_mfma_f32_16x16x32_bf16 v[54:57], v[182:185], v[218:221], v[54:57]
	v_mfma_f32_16x16x32_bf16 v[50:53], v[190:193], v[218:221], v[50:53]
	v_mfma_f32_16x16x32_bf16 v[38:41], v[182:185], v[226:229], v[38:41]
	v_mfma_f32_16x16x32_bf16 v[34:37], v[190:193], v[226:229], v[34:37]
	v_mfma_f32_16x16x32_bf16 v[22:25], v[182:185], v[234:237], v[22:25]
	v_mfma_f32_16x16x32_bf16 v[18:21], v[190:193], v[234:237], v[18:21]
	v_mfma_f32_16x16x32_bf16 v[6:9], v[182:185], v[242:245], v[6:9]
	v_mfma_f32_16x16x32_bf16 v[2:5], v[190:193], v[242:245], v[2:5]
	s_setprio 0
	s_barrier
	s_add_i32 s65, 0, 0x18000
	v_add_u32_e32 v0, s65, v146
	s_add_i32 s69, 0, 0x1c000
	ds_read_b128 v[142:145], v0
	ds_read_b128 v[166:169], v0 offset:1024
	ds_read_b128 v[170:173], v0 offset:2048
	ds_read_b128 v[174:177], v0 offset:3072
	v_add_u32_e32 v0, s69, v146
	ds_read_b128 v[178:181], v0
	ds_read_b128 v[182:185], v0 offset:1024
	ds_read_b128 v[186:189], v0 offset:2048
	ds_read_b128 v[190:193], v0 offset:3072
	s_add_u32 s4, s10, 0x2c0000
	s_addc_u32 s5, s11, 0
	s_mov_b32 m0, s18
	v_lshl_add_u64 v[206:207], s[4:5], 0, v[130:131]
	ds_read_b128 v[198:201], v165 offset:32768
	ds_read_b128 v[218:221], v165 offset:33792
	ds_read_b128 v[222:225], v165 offset:34816
	ds_read_b128 v[226:229], v165 offset:35840
	ds_read_b128 v[230:233], v165 offset:36864
	ds_read_b128 v[234:237], v165 offset:37888
	ds_read_b128 v[238:241], v165 offset:38912
	ds_read_b128 v[242:245], v165 offset:39936
	global_load_lds_dwordx4 v[206:207], off
	v_lshl_add_u64 v[206:207], s[4:5], 0, v[134:135]
	s_mov_b32 m0, s19
	s_nop 0
	global_load_lds_dwordx4 v[206:207], off
	s_waitcnt vmcnt(8) lgkmcnt(0)
	s_barrier
	s_setprio 1
	v_mfma_f32_16x16x32_bf16 v[126:129], v[142:145], v[198:201], v[126:129]
	v_mfma_f32_16x16x32_bf16 v[122:125], v[170:173], v[198:201], v[122:125]
	v_mfma_f32_16x16x32_bf16 v[110:113], v[142:145], v[222:225], v[110:113]
	v_mfma_f32_16x16x32_bf16 v[106:109], v[170:173], v[222:225], v[106:109]
	v_mfma_f32_16x16x32_bf16 v[94:97], v[142:145], v[230:233], v[94:97]
	v_mfma_f32_16x16x32_bf16 v[90:93], v[170:173], v[230:233], v[90:93]
	v_mfma_f32_16x16x32_bf16 v[78:81], v[142:145], v[238:241], v[78:81]
	v_mfma_f32_16x16x32_bf16 v[74:77], v[170:173], v[238:241], v[74:77]
	v_mfma_f32_16x16x32_bf16 v[126:129], v[166:169], v[218:221], v[126:129]
	v_mfma_f32_16x16x32_bf16 v[122:125], v[174:177], v[218:221], v[122:125]
	v_mfma_f32_16x16x32_bf16 v[110:113], v[166:169], v[226:229], v[110:113]
	v_mfma_f32_16x16x32_bf16 v[106:109], v[174:177], v[226:229], v[106:109]
	v_mfma_f32_16x16x32_bf16 v[94:97], v[166:169], v[234:237], v[94:97]
	v_mfma_f32_16x16x32_bf16 v[90:93], v[174:177], v[234:237], v[90:93]
	v_mfma_f32_16x16x32_bf16 v[78:81], v[166:169], v[242:245], v[78:81]
	v_mfma_f32_16x16x32_bf16 v[74:77], v[174:177], v[242:245], v[74:77]
	v_mfma_f32_16x16x32_bf16 v[118:121], v[178:181], v[198:201], v[118:121]
	v_mfma_f32_16x16x32_bf16 v[114:117], v[186:189], v[198:201], v[114:117]
	v_mfma_f32_16x16x32_bf16 v[102:105], v[178:181], v[222:225], v[102:105]
	v_mfma_f32_16x16x32_bf16 v[98:101], v[186:189], v[222:225], v[98:101]
	v_mfma_f32_16x16x32_bf16 v[86:89], v[178:181], v[230:233], v[86:89]
	v_mfma_f32_16x16x32_bf16 v[82:85], v[186:189], v[230:233], v[82:85]
	v_mfma_f32_16x16x32_bf16 v[70:73], v[178:181], v[238:241], v[70:73]
	v_mfma_f32_16x16x32_bf16 v[66:69], v[186:189], v[238:241], v[66:69]
	v_mfma_f32_16x16x32_bf16 v[118:121], v[182:185], v[218:221], v[118:121]
	v_mfma_f32_16x16x32_bf16 v[114:117], v[190:193], v[218:221], v[114:117]
	v_mfma_f32_16x16x32_bf16 v[102:105], v[182:185], v[226:229], v[102:105]
	v_mfma_f32_16x16x32_bf16 v[98:101], v[190:193], v[226:229], v[98:101]
	v_mfma_f32_16x16x32_bf16 v[86:89], v[182:185], v[234:237], v[86:89]
	v_mfma_f32_16x16x32_bf16 v[82:85], v[190:193], v[234:237], v[82:85]
	v_mfma_f32_16x16x32_bf16 v[70:73], v[182:185], v[242:245], v[70:73]
	v_mfma_f32_16x16x32_bf16 v[66:69], v[190:193], v[242:245], v[66:69]
	s_setprio 0
	s_barrier
; #define PG8_STAGE(bufoff, gbase, voff) do { _Pragma("unroll") for (int _i = 0; _i < 2; ++_i) \
;         __builtin_amdgcn_global_load_lds((const unsigned*)((const char*)(gbase) + (voff)[_i]), (PG8_LAS unsigned*)(lds + (bufoff) + ldsw + _i * 8192), 16, 0, 0); } while (0)
; #define PG8_LDA(dst, b, h) do { _Pragma("unroll") for (int m = 0; m < 4; ++m) _Pragma("unroll") for (int k = 0; k < 2; ++k) dst[m][k] = *(const PG8_LAS bf16x8*)(lds + PG8_SA(b, h) + aoff + m * 2048 + k * 1024); } while (0)
; #define PG8_LDB(dst, b, h) do { _Pragma("unroll") for (int n = 0; n < 2; ++n) _Pragma("unroll") for (int k = 0; k < 2; ++k) dst[n][k] = *(const PG8_LAS bf16x8*)(lds + PG8_SB(b, h) + boff + n * 2048 + k * 1024); } while (0)
; #define PG8_WAIT_V(n) asm volatile("s_waitcnt vmcnt(" #n ")" ::: "memory")
; #define PG8_WAIT_L(n) asm volatile("s_waitcnt lgkmcnt(" #n ")" ::: "memory")
; #define PG8_BAR __builtin_amdgcn_s_barrier()
; #define PG8_SCHED __builtin_amdgcn_sched_barrier(0)
; template <class Epi, class Sched, bool ALIGN_EPI = false, bool SP2 = false>
; __device__ __forceinline__ void gemm_phase(PG8_LAS unsigned char* lds, const Gemm g, const Sched& S, const Epi& E, int wv) {
;     ...
;         for (int t = 0; t < nt; t += 2) {
;     ...
;             if constexpr (SP2) {
;             PG8_LDB(B0, 0, 0); PG8_LDB(B1, 0, 1); PG8_SCHED; PG8_LDA(At, 0, 0); PG8_STAGE(PG8_SA(1, 1), a1 + hstepA, voffA);
;             PG8_WAIT_V(8); PG8_WAIT_L(0); PG8_BAR; PG8_MMA(0, 0, At, B0); PG8_MMA(0, 1, At, B1); PG8_BAR; PG8_SCHED;
;             PG8_LDA(At, 0, 1); PG8_STAGE(PG8_SB(0, 0), b2, voffB); PG8_STAGE(PG8_SB(0, 1), b2 + hstepB, voffB); PG8_STAGE(PG8_SA(0, 0), a2, voffA);
;             PG8_WAIT_V(8); PG8_WAIT_L(0); PG8_BAR; PG8_MMA(1, 0, At, B0); PG8_MMA(1, 1, At, B1); PG8_BAR; PG8_SCHED;
;             PG8_LDB(B0, 1, 0); PG8_LDB(B1, 1, 1); PG8_SCHED; PG8_LDA(At, 1, 0); PG8_STAGE(PG8_SA(0, 1), a2 + hstepA, voffA);
;             PG8_WAIT_V(8); PG8_WAIT_L(0); PG8_BAR; PG8_MMA(0, 0, At, B0); PG8_MMA(0, 1, At, B1); PG8_BAR; PG8_SCHED;
;             PG8_LDA(At, 1, 1); PG8_STAGE(PG8_SB(1, 0), b3, voffB); PG8_STAGE(PG8_SB(1, 1), b3 + hstepB, voffB); PG8_STAGE(PG8_SA(1, 0), a3, voffA);
;             PG8_WAIT_V(8); PG8_WAIT_L(0); PG8_BAR; PG8_MMA(1, 0, At, B0); PG8_MMA(1, 1, At, B1); PG8_BAR; PG8_SCHED;
;     ...
;         if constexpr (ALIGN_EPI) { if (wr == 0) PG8_BAR; }
	s_add_i32 s4, s65, s14
	v_lshl_add_u64 v[194:195], v[194:195], 0, s[20:21]
	s_mov_b32 m0, s4
	ds_read_b128 v[198:201], v165 offset:49152
	ds_read_b128 v[218:221], v165 offset:50176
	ds_read_b128 v[222:225], v165 offset:51200
	ds_read_b128 v[226:229], v165 offset:52224
	ds_read_b128 v[230:233], v165 offset:53248
	ds_read_b128 v[234:237], v165 offset:54272
	ds_read_b128 v[238:241], v165 offset:55296
	ds_read_b128 v[242:245], v165 offset:56320
	global_load_lds_dwordx4 v[194:195], off
	s_add_i32 m0, s4, 0x2000
	s_add_u32 s4, s8, 0x40080
	v_lshl_add_u64 v[194:195], v[196:197], 0, s[20:21]
	s_addc_u32 s5, s9, 0
	s_add_i32 s8, s69, s14
	global_load_lds_dwordx4 v[194:195], off
	v_lshl_add_u64 v[194:195], s[4:5], 0, v[132:133]
	s_mov_b32 m0, s8
	s_nop 0
	global_load_lds_dwordx4 v[194:195], off
	v_lshl_add_u64 v[194:195], s[4:5], 0, v[136:137]
	s_add_i32 m0, s8, 0x2000
	s_nop 0
	global_load_lds_dwordx4 v[194:195], off
	v_lshl_add_u64 v[194:195], v[202:203], 0, s[20:21]
	s_mov_b32 m0, s25
	s_nop 0
	global_load_lds_dwordx4 v[194:195], off
	v_lshl_add_u64 v[194:195], v[204:205], 0, s[20:21]
	s_mov_b32 m0, s46
	s_nop 0
	global_load_lds_dwordx4 v[194:195], off
	s_waitcnt vmcnt(8) lgkmcnt(0)
	s_barrier
	s_setprio 1
	v_mfma_f32_16x16x32_bf16 v[62:65], v[142:145], v[198:201], v[62:65]
	v_mfma_f32_16x16x32_bf16 v[58:61], v[170:173], v[198:201], v[58:61]
	v_mfma_f32_16x16x32_bf16 v[46:49], v[142:145], v[222:225], v[46:49]
	v_mfma_f32_16x16x32_bf16 v[42:45], v[170:173], v[222:225], v[42:45]
	v_mfma_f32_16x16x32_bf16 v[30:33], v[142:145], v[230:233], v[30:33]
	v_mfma_f32_16x16x32_bf16 v[26:29], v[170:173], v[230:233], v[26:29]
	v_mfma_f32_16x16x32_bf16 v[14:17], v[142:145], v[238:241], v[14:17]
	v_mfma_f32_16x16x32_bf16 v[10:13], v[170:173], v[238:241], v[10:13]
	v_mfma_f32_16x16x32_bf16 v[62:65], v[166:169], v[218:221], v[62:65]
	v_mfma_f32_16x16x32_bf16 v[58:61], v[174:177], v[218:221], v[58:61]
	v_mfma_f32_16x16x32_bf16 v[46:49], v[166:169], v[226:229], v[46:49]
	v_mfma_f32_16x16x32_bf16 v[42:45], v[174:177], v[226:229], v[42:45]
	v_mfma_f32_16x16x32_bf16 v[30:33], v[166:169], v[234:237], v[30:33]
	v_mfma_f32_16x16x32_bf16 v[26:29], v[174:177], v[234:237], v[26:29]
	v_mfma_f32_16x16x32_bf16 v[14:17], v[166:169], v[242:245], v[14:17]
	v_mfma_f32_16x16x32_bf16 v[10:13], v[174:177], v[242:245], v[10:13]
	v_mfma_f32_16x16x32_bf16 v[54:57], v[178:181], v[198:201], v[54:57]
	v_mfma_f32_16x16x32_bf16 v[50:53], v[186:189], v[198:201], v[50:53]
	v_mfma_f32_16x16x32_bf16 v[38:41], v[178:181], v[222:225], v[38:41]
	v_mfma_f32_16x16x32_bf16 v[34:37], v[186:189], v[222:225], v[34:37]
	v_mfma_f32_16x16x32_bf16 v[22:25], v[178:181], v[230:233], v[22:25]
	v_mfma_f32_16x16x32_bf16 v[18:21], v[186:189], v[230:233], v[18:21]
	v_mfma_f32_16x16x32_bf16 v[6:9], v[178:181], v[238:241], v[6:9]
	v_mfma_f32_16x16x32_bf16 v[2:5], v[186:189], v[238:241], v[2:5]
	v_mfma_f32_16x16x32_bf16 v[54:57], v[182:185], v[218:221], v[54:57]
	v_mfma_f32_16x16x32_bf16 v[50:53], v[190:193], v[218:221], v[50:53]
	v_mfma_f32_16x16x32_bf16 v[38:41], v[182:185], v[226:229], v[38:41]
	v_mfma_f32_16x16x32_bf16 v[34:37], v[190:193], v[226:229], v[34:37]
	v_mfma_f32_16x16x32_bf16 v[22:25], v[182:185], v[234:237], v[22:25]
	v_mfma_f32_16x16x32_bf16 v[18:21], v[190:193], v[234:237], v[18:21]
	v_mfma_f32_16x16x32_bf16 v[6:9], v[182:185], v[242:245], v[6:9]
	v_mfma_f32_16x16x32_bf16 v[2:5], v[190:193], v[242:245], v[2:5]
	s_setprio 0
	s_barrier
	s_add_i32 s37, s37, 2
	s_add_u32 s33, s33, 0x100
	s_addc_u32 s36, s36, 0
	s_cmp_gt_u32 s37, 13
	s_mov_b64 s[4:5], s[6:7]
	s_cbranch_scc0 .LBB0_140
	s_and_b64 vcc, exec, s[2:3]
	s_cbranch_vccz .LBB0_143
	s_barrier

; #define PG8_STAGE(bufoff, gbase, voff) do { _Pragma("unroll") for (int _i = 0; _i < 2; ++_i) \
;         __builtin_amdgcn_global_load_lds((const unsigned*)((const char*)(gbase) + (voff)[_i]), (PG8_LAS unsigned*)(lds + (bufoff) + ldsw + _i * 8192), 16, 0, 0); } while (0)
; #define PG8_LDA(dst, b, h) do { _Pragma("unroll") for (int m = 0; m < 4; ++m) _Pragma("unroll") for (int k = 0; k < 2; ++k) dst[m][k] = *(const PG8_LAS bf16x8*)(lds + PG8_SA(b, h) + aoff + m * 2048 + k * 1024); } while (0)
; #define PG8_LDB(dst, b, h) do { _Pragma("unroll") for (int n = 0; n < 2; ++n) _Pragma("unroll") for (int k = 0; k < 2; ++k) dst[n][k] = *(const PG8_LAS bf16x8*)(lds + PG8_SB(b, h) + boff + n * 2048 + k * 1024); } while (0)
; #define PG8_MMA(ai, bj, At, Bt) do { __builtin_amdgcn_s_setprio(1); _Pragma("unroll") for (int m = 0; m < 4; ++m) _Pragma("unroll") for (int n = 0; n < 2; ++n) _Pragma("unroll") for (int k = 0; k < 2; ++k) \
;         acc[ai][bj][m][n] = __builtin_amdgcn_mfma_f32_16x16x32_bf16(Bt[n][k], At[m][k], acc[ai][bj][m][n], 0, 0, 0); __builtin_amdgcn_s_setprio(0); } while (0)
; template <class Epi, class Sched, bool ALIGN_EPI = false, bool SP2 = false>
; __device__ __forceinline__ void gemm_phase(PG8_LAS unsigned char* lds, const Gemm g, const Sched& S, const Epi& E, int wv) {
;     ...
;             if constexpr (SP2) {
;             PG8_LDB(B0, 0, 0); PG8_LDB(B1, 0, 1); PG8_SCHED; PG8_LDA(At, 0, 0); PG8_STAGE(PG8_SA(1, 1), a1 + hstepA, voffA);
;             PG8_WAIT_V(8); PG8_WAIT_L(0); PG8_BAR; PG8_MMA(0, 0, At, B0); PG8_MMA(0, 1, At, B1); PG8_BAR; PG8_SCHED;
;             PG8_LDA(At, 0, 1); PG8_STAGE(PG8_SB(0, 0), b2, voffB); PG8_STAGE(PG8_SB(0, 1), b2 + hstepB, voffB); PG8_STAGE(PG8_SA(0, 0), a2, voffA);
;             PG8_WAIT_V(8); PG8_WAIT_L(0); PG8_BAR; PG8_MMA(1, 0, At, B0); PG8_MMA(1, 1, At, B1); PG8_BAR; PG8_SCHED;
;             PG8_LDB(B0, 1, 0); PG8_LDB(B1, 1, 1); PG8_SCHED; PG8_LDA(At, 1, 0); PG8_STAGE(PG8_SA(0, 1), a2 + hstepA, voffA);
;             PG8_WAIT_V(8); PG8_WAIT_L(0); PG8_BAR; PG8_MMA(0, 0, At, B0); PG8_MMA(0, 1, At, B1); PG8_BAR; PG8_SCHED;
;             PG8_LDA(At, 1, 1); PG8_STAGE(PG8_SB(1, 0), b3, voffB); PG8_STAGE(PG8_SB(1, 1), b3 + hstepB, voffB); PG8_STAGE(PG8_SA(1, 0), a3, voffA);
;             PG8_WAIT_V(8); PG8_WAIT_L(0); PG8_BAR; PG8_MMA(1, 0, At, B0); PG8_MMA(1, 1, At, B1); PG8_BAR; PG8_SCHED;
.LBB0_266:
	s_add_u32 s14, s12, 0xfffc0080
	s_addc_u32 s15, s13, -1
	s_add_i32 s41, 0, 0x10000
	s_cmp_eq_u32 s40, 12
	s_cselect_b32 s17, s5, s15
	s_cselect_b32 s16, s18, s14
	v_add_u32_e32 v146, s41, v154
	s_cselect_b32 s15, s7, s39
	s_cselect_b32 s14, s19, s38
	s_add_i32 s46, 0, 0x14000
	ds_read_b128 v[148:151], v146
	ds_read_b128 v[164:167], v146 offset:1024
	ds_read_b128 v[168:171], v146 offset:2048
	ds_read_b128 v[172:175], v146 offset:3072
	v_add_u32_e32 v146, s46, v154
	ds_read_b128 v[176:179], v146
	ds_read_b128 v[180:183], v146 offset:1024
	ds_read_b128 v[184:187], v146 offset:2048
	ds_read_b128 v[188:191], v146 offset:3072
	v_lshl_add_u64 v[152:153], s[12:13], 0, v[142:143]
	s_add_i32 m0, s43, 0xc000
	ds_read_b128 v[198:201], v163
	ds_read_b128 v[218:221], v163 offset:1024
	ds_read_b128 v[222:225], v163 offset:2048
	ds_read_b128 v[226:229], v163 offset:3072
	ds_read_b128 v[230:233], v163 offset:4096
	ds_read_b128 v[234:237], v163 offset:5120
	ds_read_b128 v[238:241], v163 offset:6144
	ds_read_b128 v[242:245], v163 offset:7168
	global_load_lds_dwordx4 v[152:153], off
	v_lshl_add_u64 v[152:153], s[12:13], 0, v[144:145]
	s_add_i32 m0, s43, 0xe000
	s_nop 0
	global_load_lds_dwordx4 v[152:153], off
	s_waitcnt vmcnt(8) lgkmcnt(0)
	s_barrier
	s_setprio 1
	v_mfma_f32_16x16x32_bf16 v[126:129], v[148:151], v[198:201], v[126:129]
	v_mfma_f32_16x16x32_bf16 v[122:125], v[168:171], v[198:201], v[122:125]
	v_mfma_f32_16x16x32_bf16 v[110:113], v[148:151], v[222:225], v[110:113]
	v_mfma_f32_16x16x32_bf16 v[106:109], v[168:171], v[222:225], v[106:109]
	v_mfma_f32_16x16x32_bf16 v[94:97], v[148:151], v[230:233], v[94:97]
	v_mfma_f32_16x16x32_bf16 v[90:93], v[168:171], v[230:233], v[90:93]
	v_mfma_f32_16x16x32_bf16 v[78:81], v[148:151], v[238:241], v[78:81]
	v_mfma_f32_16x16x32_bf16 v[74:77], v[168:171], v[238:241], v[74:77]
	v_mfma_f32_16x16x32_bf16 v[126:129], v[164:167], v[218:221], v[126:129]
	v_mfma_f32_16x16x32_bf16 v[122:125], v[172:175], v[218:221], v[122:125]
	v_mfma_f32_16x16x32_bf16 v[110:113], v[164:167], v[226:229], v[110:113]
	v_mfma_f32_16x16x32_bf16 v[106:109], v[172:175], v[226:229], v[106:109]
	v_mfma_f32_16x16x32_bf16 v[94:97], v[164:167], v[234:237], v[94:97]
	v_mfma_f32_16x16x32_bf16 v[90:93], v[172:175], v[234:237], v[90:93]
	v_mfma_f32_16x16x32_bf16 v[78:81], v[164:167], v[242:245], v[78:81]
	v_mfma_f32_16x16x32_bf16 v[74:77], v[172:175], v[242:245], v[74:77]
	v_mfma_f32_16x16x32_bf16 v[118:121], v[176:179], v[198:201], v[118:121]
	v_mfma_f32_16x16x32_bf16 v[114:117], v[184:187], v[198:201], v[114:117]
	v_mfma_f32_16x16x32_bf16 v[102:105], v[176:179], v[222:225], v[102:105]
	v_mfma_f32_16x16x32_bf16 v[98:101], v[184:187], v[222:225], v[98:101]
	v_mfma_f32_16x16x32_bf16 v[86:89], v[176:179], v[230:233], v[86:89]
	v_mfma_f32_16x16x32_bf16 v[82:85], v[184:187], v[230:233], v[82:85]
	v_mfma_f32_16x16x32_bf16 v[70:73], v[176:179], v[238:241], v[70:73]
	v_mfma_f32_16x16x32_bf16 v[66:69], v[184:187], v[238:241], v[66:69]
	v_mfma_f32_16x16x32_bf16 v[118:121], v[180:183], v[218:221], v[118:121]
	v_mfma_f32_16x16x32_bf16 v[114:117], v[188:191], v[218:221], v[114:117]
	v_mfma_f32_16x16x32_bf16 v[102:105], v[180:183], v[226:229], v[102:105]
	v_mfma_f32_16x16x32_bf16 v[98:101], v[188:191], v[226:229], v[98:101]
	v_mfma_f32_16x16x32_bf16 v[86:89], v[180:183], v[234:237], v[86:89]
	v_mfma_f32_16x16x32_bf16 v[82:85], v[188:191], v[234:237], v[82:85]
	v_mfma_f32_16x16x32_bf16 v[70:73], v[180:183], v[242:245], v[70:73]
	v_mfma_f32_16x16x32_bf16 v[66:69], v[188:191], v[242:245], v[66:69]
	s_setprio 0
	s_barrier
	s_add_i32 s41, s41, s79
	v_lshl_add_u64 v[152:153], s[14:15], 0, v[132:133]
	s_mov_b32 m0, s41
	ds_read_b128 v[198:201], v163 offset:16384
	ds_read_b128 v[218:221], v163 offset:17408
	ds_read_b128 v[222:225], v163 offset:18432
	ds_read_b128 v[226:229], v163 offset:19456
	ds_read_b128 v[230:233], v163 offset:20480
	ds_read_b128 v[234:237], v163 offset:21504
	ds_read_b128 v[238:241], v163 offset:22528
	ds_read_b128 v[242:245], v163 offset:23552
	global_load_lds_dwordx4 v[152:153], off
	s_add_i32 m0, s41, 0x2000
	s_add_u32 vcc_lo, s14, 0x40000
	v_lshl_add_u64 v[192:193], s[14:15], 0, v[136:137]
	s_addc_u32 vcc_hi, s15, 0
	s_add_i32 s41, s46, s79
	global_load_lds_dwordx4 v[192:193], off
	v_lshl_add_u64 v[194:195], vcc, 0, v[132:133]
	s_mov_b32 m0, s41
	v_lshl_add_u64 v[196:197], s[16:17], 0, v[134:135]
	global_load_lds_dwordx4 v[194:195], off
	v_lshl_add_u64 v[194:195], vcc, 0, v[136:137]
	s_add_i32 m0, s41, 0x2000
	s_nop 0
	global_load_lds_dwordx4 v[194:195], off
	v_lshl_add_u64 v[194:195], s[16:17], 0, v[130:131]
	s_mov_b32 m0, s43
	s_nop 0
	global_load_lds_dwordx4 v[194:195], off
	s_mov_b32 m0, s65
	s_nop 0
	global_load_lds_dwordx4 v[196:197], off
	s_waitcnt vmcnt(8) lgkmcnt(0)
	s_barrier
; #define PG8_STAGE(bufoff, gbase, voff) do { _Pragma("unroll") for (int _i = 0; _i < 2; ++_i) \
;         __builtin_amdgcn_global_load_lds((const unsigned*)((const char*)(gbase) + (voff)[_i]), (PG8_LAS unsigned*)(lds + (bufoff) + ldsw + _i * 8192), 16, 0, 0); } while (0)
; #define PG8_LDA(dst, b, h) do { _Pragma("unroll") for (int m = 0; m < 4; ++m) _Pragma("unroll") for (int k = 0; k < 2; ++k) dst[m][k] = *(const PG8_LAS bf16x8*)(lds + PG8_SA(b, h) + aoff + m * 2048 + k * 1024); } while (0)
; #define PG8_LDB(dst, b, h) do { _Pragma("unroll") for (int n = 0; n < 2; ++n) _Pragma("unroll") for (int k = 0; k < 2; ++k) dst[n][k] = *(const PG8_LAS bf16x8*)(lds + PG8_SB(b, h) + boff + n * 2048 + k * 1024); } while (0)
; #define PG8_MMA(ai, bj, At, Bt) do { __builtin_amdgcn_s_setprio(1); _Pragma("unroll") for (int m = 0; m < 4; ++m) _Pragma("unroll") for (int n = 0; n < 2; ++n) _Pragma("unroll") for (int k = 0; k < 2; ++k) \
;         acc[ai][bj][m][n] = __builtin_amdgcn_mfma_f32_16x16x32_bf16(Bt[n][k], At[m][k], acc[ai][bj][m][n], 0, 0, 0); __builtin_amdgcn_s_setprio(0); } while (0)
; template <class Epi, class Sched, bool ALIGN_EPI = false, bool SP2 = false>
; __device__ __forceinline__ void gemm_phase(PG8_LAS unsigned char* lds, const Gemm g, const Sched& S, const Epi& E, int wv) {
;     ...
;             if constexpr (SP2) {
;             PG8_LDB(B0, 0, 0); PG8_LDB(B1, 0, 1); PG8_SCHED; PG8_LDA(At, 0, 0); PG8_STAGE(PG8_SA(1, 1), a1 + hstepA, voffA);
;             PG8_WAIT_V(8); PG8_WAIT_L(0); PG8_BAR; PG8_MMA(0, 0, At, B0); PG8_MMA(0, 1, At, B1); PG8_BAR; PG8_SCHED;
;             PG8_LDA(At, 0, 1); PG8_STAGE(PG8_SB(0, 0), b2, voffB); PG8_STAGE(PG8_SB(0, 1), b2 + hstepB, voffB); PG8_STAGE(PG8_SA(0, 0), a2, voffA);
;             PG8_WAIT_V(8); PG8_WAIT_L(0); PG8_BAR; PG8_MMA(1, 0, At, B0); PG8_MMA(1, 1, At, B1); PG8_BAR; PG8_SCHED;
;             PG8_LDB(B0, 1, 0); PG8_LDB(B1, 1, 1); PG8_SCHED; PG8_LDA(At, 1, 0); PG8_STAGE(PG8_SA(0, 1), a2 + hstepA, voffA);
;             PG8_WAIT_V(8); PG8_WAIT_L(0); PG8_BAR; PG8_MMA(0, 0, At, B0); PG8_MMA(0, 1, At, B1); PG8_BAR; PG8_SCHED;
;             PG8_LDA(At, 1, 1); PG8_STAGE(PG8_SB(1, 0), b3, voffB); PG8_STAGE(PG8_SB(1, 1), b3 + hstepB, voffB); PG8_STAGE(PG8_SA(1, 0), a3, voffA);
;             PG8_WAIT_V(8); PG8_WAIT_L(0); PG8_BAR; PG8_MMA(1, 0, At, B0); PG8_MMA(1, 1, At, B1); PG8_BAR; PG8_SCHED;
	s_setprio 1
	v_mfma_f32_16x16x32_bf16 v[62:65], v[148:151], v[198:201], v[62:65]
	v_mfma_f32_16x16x32_bf16 v[58:61], v[168:171], v[198:201], v[58:61]
	v_mfma_f32_16x16x32_bf16 v[46:49], v[148:151], v[222:225], v[46:49]
	v_mfma_f32_16x16x32_bf16 v[42:45], v[168:171], v[222:225], v[42:45]
	v_mfma_f32_16x16x32_bf16 v[30:33], v[148:151], v[230:233], v[30:33]
	v_mfma_f32_16x16x32_bf16 v[26:29], v[168:171], v[230:233], v[26:29]
	v_mfma_f32_16x16x32_bf16 v[14:17], v[148:151], v[238:241], v[14:17]
	v_mfma_f32_16x16x32_bf16 v[10:13], v[168:171], v[238:241], v[10:13]
	v_mfma_f32_16x16x32_bf16 v[62:65], v[164:167], v[218:221], v[62:65]
	v_mfma_f32_16x16x32_bf16 v[58:61], v[172:175], v[218:221], v[58:61]
	v_mfma_f32_16x16x32_bf16 v[46:49], v[164:167], v[226:229], v[46:49]
	v_mfma_f32_16x16x32_bf16 v[42:45], v[172:175], v[226:229], v[42:45]
	v_mfma_f32_16x16x32_bf16 v[30:33], v[164:167], v[234:237], v[30:33]
	v_mfma_f32_16x16x32_bf16 v[26:29], v[172:175], v[234:237], v[26:29]
	v_mfma_f32_16x16x32_bf16 v[14:17], v[164:167], v[242:245], v[14:17]
	v_mfma_f32_16x16x32_bf16 v[10:13], v[172:175], v[242:245], v[10:13]
	v_mfma_f32_16x16x32_bf16 v[54:57], v[176:179], v[198:201], v[54:57]
	v_mfma_f32_16x16x32_bf16 v[50:53], v[184:187], v[198:201], v[50:53]
	v_mfma_f32_16x16x32_bf16 v[38:41], v[176:179], v[222:225], v[38:41]
	v_mfma_f32_16x16x32_bf16 v[34:37], v[184:187], v[222:225], v[34:37]
	v_mfma_f32_16x16x32_bf16 v[22:25], v[176:179], v[230:233], v[22:25]
	v_mfma_f32_16x16x32_bf16 v[18:21], v[184:187], v[230:233], v[18:21]
	v_mfma_f32_16x16x32_bf16 v[6:9], v[176:179], v[238:241], v[6:9]
	v_mfma_f32_16x16x32_bf16 v[2:5], v[184:187], v[238:241], v[2:5]
	v_mfma_f32_16x16x32_bf16 v[54:57], v[180:183], v[218:221], v[54:57]
	v_mfma_f32_16x16x32_bf16 v[50:53], v[188:191], v[218:221], v[50:53]
	v_mfma_f32_16x16x32_bf16 v[38:41], v[180:183], v[226:229], v[38:41]
	v_mfma_f32_16x16x32_bf16 v[34:37], v[188:191], v[226:229], v[34:37]
	v_mfma_f32_16x16x32_bf16 v[22:25], v[180:183], v[234:237], v[22:25]
	v_mfma_f32_16x16x32_bf16 v[18:21], v[188:191], v[234:237], v[18:21]
	v_mfma_f32_16x16x32_bf16 v[6:9], v[180:183], v[242:245], v[6:9]
	v_mfma_f32_16x16x32_bf16 v[2:5], v[188:191], v[242:245], v[2:5]
	s_setprio 0
	s_barrier
	s_add_i32 s41, 0, 0x18000
	v_add_u32_e32 v146, s41, v154
	s_add_i32 s46, 0, 0x1c000
	ds_read_b128 v[148:151], v146
	ds_read_b128 v[164:167], v146 offset:1024
	ds_read_b128 v[168:171], v146 offset:2048
	ds_read_b128 v[172:175], v146 offset:3072
	v_add_u32_e32 v146, s46, v154
	ds_read_b128 v[176:179], v146
	ds_read_b128 v[180:183], v146 offset:1024
	ds_read_b128 v[184:187], v146 offset:2048
	ds_read_b128 v[188:191], v146 offset:3072
	s_add_u32 s16, s16, 0x40000
	s_addc_u32 s17, s17, 0
	s_mov_b32 m0, s24
	v_lshl_add_u64 v[202:203], s[16:17], 0, v[130:131]
	ds_read_b128 v[198:201], v163 offset:32768
	ds_read_b128 v[218:221], v163 offset:33792
	ds_read_b128 v[222:225], v163 offset:34816
	ds_read_b128 v[226:229], v163 offset:35840
	ds_read_b128 v[230:233], v163 offset:36864
	ds_read_b128 v[234:237], v163 offset:37888
	ds_read_b128 v[238:241], v163 offset:38912
	ds_read_b128 v[242:245], v163 offset:39936
	global_load_lds_dwordx4 v[202:203], off
	v_lshl_add_u64 v[202:203], s[16:17], 0, v[134:135]
	s_mov_b32 m0, s77
	s_nop 0
	global_load_lds_dwordx4 v[202:203], off
	s_waitcnt vmcnt(8) lgkmcnt(0)
	s_barrier
	s_setprio 1
	v_mfma_f32_16x16x32_bf16 v[126:129], v[148:151], v[198:201], v[126:129]
	v_mfma_f32_16x16x32_bf16 v[122:125], v[168:171], v[198:201], v[122:125]
	v_mfma_f32_16x16x32_bf16 v[110:113], v[148:151], v[222:225], v[110:113]
	v_mfma_f32_16x16x32_bf16 v[106:109], v[168:171], v[222:225], v[106:109]
	v_mfma_f32_16x16x32_bf16 v[94:97], v[148:151], v[230:233], v[94:97]
	v_mfma_f32_16x16x32_bf16 v[90:93], v[168:171], v[230:233], v[90:93]
	v_mfma_f32_16x16x32_bf16 v[78:81], v[148:151], v[238:241], v[78:81]
	v_mfma_f32_16x16x32_bf16 v[74:77], v[168:171], v[238:241], v[74:77]
	v_mfma_f32_16x16x32_bf16 v[126:129], v[164:167], v[218:221], v[126:129]
	v_mfma_f32_16x16x32_bf16 v[122:125], v[172:175], v[218:221], v[122:125]
	v_mfma_f32_16x16x32_bf16 v[110:113], v[164:167], v[226:229], v[110:113]
	v_mfma_f32_16x16x32_bf16 v[106:109], v[172:175], v[226:229], v[106:109]
	v_mfma_f32_16x16x32_bf16 v[94:97], v[164:167], v[234:237], v[94:97]
	v_mfma_f32_16x16x32_bf16 v[90:93], v[172:175], v[234:237], v[90:93]
	v_mfma_f32_16x16x32_bf16 v[78:81], v[164:167], v[242:245], v[78:81]
	v_mfma_f32_16x16x32_bf16 v[74:77], v[172:175], v[242:245], v[74:77]
	v_mfma_f32_16x16x32_bf16 v[118:121], v[176:179], v[198:201], v[118:121]
	v_mfma_f32_16x16x32_bf16 v[114:117], v[184:187], v[198:201], v[114:117]
	v_mfma_f32_16x16x32_bf16 v[102:105], v[176:179], v[222:225], v[102:105]
	v_mfma_f32_16x16x32_bf16 v[98:101], v[184:187], v[222:225], v[98:101]
	v_mfma_f32_16x16x32_bf16 v[86:89], v[176:179], v[230:233], v[86:89]
	v_mfma_f32_16x16x32_bf16 v[82:85], v[184:187], v[230:233], v[82:85]
	v_mfma_f32_16x16x32_bf16 v[70:73], v[176:179], v[238:241], v[70:73]
	v_mfma_f32_16x16x32_bf16 v[66:69], v[184:187], v[238:241], v[66:69]
	v_mfma_f32_16x16x32_bf16 v[118:121], v[180:183], v[218:221], v[118:121]
	v_mfma_f32_16x16x32_bf16 v[114:117], v[188:191], v[218:221], v[114:117]
	v_mfma_f32_16x16x32_bf16 v[102:105], v[180:183], v[226:229], v[102:105]
	v_mfma_f32_16x16x32_bf16 v[98:101], v[188:191], v[226:229], v[98:101]
	v_mfma_f32_16x16x32_bf16 v[86:89], v[180:183], v[234:237], v[86:89]
	v_mfma_f32_16x16x32_bf16 v[82:85], v[188:191], v[234:237], v[82:85]
	v_mfma_f32_16x16x32_bf16 v[70:73], v[180:183], v[242:245], v[70:73]
	v_mfma_f32_16x16x32_bf16 v[66:69], v[188:191], v[242:245], v[66:69]
	s_setprio 0
	s_barrier
; #define PG8_STAGE(bufoff, gbase, voff) do { _Pragma("unroll") for (int _i = 0; _i < 2; ++_i) \
;         __builtin_amdgcn_global_load_lds((const unsigned*)((const char*)(gbase) + (voff)[_i]), (PG8_LAS unsigned*)(lds + (bufoff) + ldsw + _i * 8192), 16, 0, 0); } while (0)
; #define PG8_LDA(dst, b, h) do { _Pragma("unroll") for (int m = 0; m < 4; ++m) _Pragma("unroll") for (int k = 0; k < 2; ++k) dst[m][k] = *(const PG8_LAS bf16x8*)(lds + PG8_SA(b, h) + aoff + m * 2048 + k * 1024); } while (0)
; #define PG8_LDB(dst, b, h) do { _Pragma("unroll") for (int n = 0; n < 2; ++n) _Pragma("unroll") for (int k = 0; k < 2; ++k) dst[n][k] = *(const PG8_LAS bf16x8*)(lds + PG8_SB(b, h) + boff + n * 2048 + k * 1024); } while (0)
; #define PG8_WAIT_V(n) asm volatile("s_waitcnt vmcnt(" #n ")" ::: "memory")
; #define PG8_WAIT_L(n) asm volatile("s_waitcnt lgkmcnt(" #n ")" ::: "memory")
; #define PG8_BAR __builtin_amdgcn_s_barrier()
; #define PG8_SCHED __builtin_amdgcn_sched_barrier(0)
; template <class Epi, class Sched, bool ALIGN_EPI = false, bool SP2 = false>
; __device__ __forceinline__ void gemm_phase(PG8_LAS unsigned char* lds, const Gemm g, const Sched& S, const Epi& E, int wv) {
;     ...
;         for (int t = 0; t < nt; t += 2) {
;     ...
;             if constexpr (SP2) {
;             PG8_LDB(B0, 0, 0); PG8_LDB(B1, 0, 1); PG8_SCHED; PG8_LDA(At, 0, 0); PG8_STAGE(PG8_SA(1, 1), a1 + hstepA, voffA);
;             PG8_WAIT_V(8); PG8_WAIT_L(0); PG8_BAR; PG8_MMA(0, 0, At, B0); PG8_MMA(0, 1, At, B1); PG8_BAR; PG8_SCHED;
;             PG8_LDA(At, 0, 1); PG8_STAGE(PG8_SB(0, 0), b2, voffB); PG8_STAGE(PG8_SB(0, 1), b2 + hstepB, voffB); PG8_STAGE(PG8_SA(0, 0), a2, voffA);
;             PG8_WAIT_V(8); PG8_WAIT_L(0); PG8_BAR; PG8_MMA(1, 0, At, B0); PG8_MMA(1, 1, At, B1); PG8_BAR; PG8_SCHED;
;             PG8_LDB(B0, 1, 0); PG8_LDB(B1, 1, 1); PG8_SCHED; PG8_LDA(At, 1, 0); PG8_STAGE(PG8_SA(0, 1), a2 + hstepA, voffA);
;             PG8_WAIT_V(8); PG8_WAIT_L(0); PG8_BAR; PG8_MMA(0, 0, At, B0); PG8_MMA(0, 1, At, B1); PG8_BAR; PG8_SCHED;
;             PG8_LDA(At, 1, 1); PG8_STAGE(PG8_SB(1, 0), b3, voffB); PG8_STAGE(PG8_SB(1, 1), b3 + hstepB, voffB); PG8_STAGE(PG8_SA(1, 0), a3, voffA);
;             PG8_WAIT_V(8); PG8_WAIT_L(0); PG8_BAR; PG8_MMA(1, 0, At, B0); PG8_MMA(1, 1, At, B1); PG8_BAR; PG8_SCHED;
;     ...
;         if constexpr (ALIGN_EPI) { if (wr == 0) PG8_BAR; }
	s_add_i32 s16, s41, s79
	v_lshl_add_u64 v[152:153], v[152:153], 0, s[20:21]
	s_mov_b32 m0, s16
	ds_read_b128 v[198:201], v163 offset:49152
	ds_read_b128 v[218:221], v163 offset:50176
	ds_read_b128 v[222:225], v163 offset:51200
	ds_read_b128 v[226:229], v163 offset:52224
	ds_read_b128 v[230:233], v163 offset:53248
	ds_read_b128 v[234:237], v163 offset:54272
	ds_read_b128 v[238:241], v163 offset:55296
	ds_read_b128 v[242:245], v163 offset:56320
	global_load_lds_dwordx4 v[152:153], off
	s_add_i32 m0, s16, 0x2000
	s_add_u32 s14, s14, 0x40080
	v_lshl_add_u64 v[152:153], v[192:193], 0, s[20:21]
	s_addc_u32 s15, s15, 0
	s_add_i32 s16, s46, s79
	global_load_lds_dwordx4 v[152:153], off
	v_lshl_add_u64 v[152:153], s[14:15], 0, v[132:133]
	s_mov_b32 m0, s16
	s_nop 0
	global_load_lds_dwordx4 v[152:153], off
	v_lshl_add_u64 v[152:153], s[14:15], 0, v[136:137]
	s_add_i32 m0, s16, 0x2000
	s_nop 0
	global_load_lds_dwordx4 v[152:153], off
	v_lshl_add_u64 v[152:153], v[194:195], 0, s[20:21]
	s_mov_b32 m0, s30
	s_nop 0
	global_load_lds_dwordx4 v[152:153], off
	v_lshl_add_u64 v[152:153], v[196:197], 0, s[20:21]
	s_mov_b32 m0, s31
	s_nop 0
	global_load_lds_dwordx4 v[152:153], off
	s_waitcnt vmcnt(8) lgkmcnt(0)
	s_barrier
	s_setprio 1
	v_mfma_f32_16x16x32_bf16 v[62:65], v[148:151], v[198:201], v[62:65]
	v_mfma_f32_16x16x32_bf16 v[58:61], v[168:171], v[198:201], v[58:61]
	v_mfma_f32_16x16x32_bf16 v[46:49], v[148:151], v[222:225], v[46:49]
	v_mfma_f32_16x16x32_bf16 v[42:45], v[168:171], v[222:225], v[42:45]
	v_mfma_f32_16x16x32_bf16 v[30:33], v[148:151], v[230:233], v[30:33]
	v_mfma_f32_16x16x32_bf16 v[26:29], v[168:171], v[230:233], v[26:29]
	v_mfma_f32_16x16x32_bf16 v[14:17], v[148:151], v[238:241], v[14:17]
	v_mfma_f32_16x16x32_bf16 v[10:13], v[168:171], v[238:241], v[10:13]
	v_mfma_f32_16x16x32_bf16 v[62:65], v[164:167], v[218:221], v[62:65]
	v_mfma_f32_16x16x32_bf16 v[58:61], v[172:175], v[218:221], v[58:61]
	v_mfma_f32_16x16x32_bf16 v[46:49], v[164:167], v[226:229], v[46:49]
	v_mfma_f32_16x16x32_bf16 v[42:45], v[172:175], v[226:229], v[42:45]
	v_mfma_f32_16x16x32_bf16 v[30:33], v[164:167], v[234:237], v[30:33]
	v_mfma_f32_16x16x32_bf16 v[26:29], v[172:175], v[234:237], v[26:29]
	v_mfma_f32_16x16x32_bf16 v[14:17], v[164:167], v[242:245], v[14:17]
	v_mfma_f32_16x16x32_bf16 v[10:13], v[172:175], v[242:245], v[10:13]
	v_mfma_f32_16x16x32_bf16 v[54:57], v[176:179], v[198:201], v[54:57]
	v_mfma_f32_16x16x32_bf16 v[50:53], v[184:187], v[198:201], v[50:53]
	v_mfma_f32_16x16x32_bf16 v[38:41], v[176:179], v[222:225], v[38:41]
	v_mfma_f32_16x16x32_bf16 v[34:37], v[184:187], v[222:225], v[34:37]
	v_mfma_f32_16x16x32_bf16 v[22:25], v[176:179], v[230:233], v[22:25]
	v_mfma_f32_16x16x32_bf16 v[18:21], v[184:187], v[230:233], v[18:21]
	v_mfma_f32_16x16x32_bf16 v[6:9], v[176:179], v[238:241], v[6:9]
	v_mfma_f32_16x16x32_bf16 v[2:5], v[184:187], v[238:241], v[2:5]
	v_mfma_f32_16x16x32_bf16 v[54:57], v[180:183], v[218:221], v[54:57]
	v_mfma_f32_16x16x32_bf16 v[50:53], v[188:191], v[218:221], v[50:53]
	v_mfma_f32_16x16x32_bf16 v[38:41], v[180:183], v[226:229], v[38:41]
	v_mfma_f32_16x16x32_bf16 v[34:37], v[188:191], v[226:229], v[34:37]
	v_mfma_f32_16x16x32_bf16 v[22:25], v[180:183], v[234:237], v[22:25]
	v_mfma_f32_16x16x32_bf16 v[18:21], v[188:191], v[234:237], v[18:21]
	v_mfma_f32_16x16x32_bf16 v[6:9], v[180:183], v[242:245], v[6:9]
	v_mfma_f32_16x16x32_bf16 v[2:5], v[188:191], v[242:245], v[2:5]
	s_setprio 0
	s_barrier
	s_add_i32 s40, s40, 2
	s_add_u32 s12, s12, 0x100
	s_addc_u32 s13, s13, 0
	s_add_u32 s38, s38, 0x100
	s_addc_u32 s39, s39, 0
	s_cmp_gt_u32 s40, 13
	s_cbranch_scc0 .LBB0_266
	s_and_b64 vcc, exec, s[2:3]
	s_cbranch_vccz .LBB0_269
	s_barrier

; #define PG8_STAGE(bufoff, gbase, voff) do { _Pragma("unroll") for (int _i = 0; _i < 2; ++_i) \
;         __builtin_amdgcn_global_load_lds((const unsigned*)((const char*)(gbase) + (voff)[_i]), (PG8_LAS unsigned*)(lds + (bufoff) + ldsw + _i * 8192), 16, 0, 0); } while (0)
; #define PG8_LDA(dst, b, h) do { _Pragma("unroll") for (int m = 0; m < 4; ++m) _Pragma("unroll") for (int k = 0; k < 2; ++k) dst[m][k] = *(const PG8_LAS bf16x8*)(lds + PG8_SA(b, h) + aoff + m * 2048 + k * 1024); } while (0)
; #define PG8_LDB(dst, b, h) do { _Pragma("unroll") for (int n = 0; n < 2; ++n) _Pragma("unroll") for (int k = 0; k < 2; ++k) dst[n][k] = *(const PG8_LAS bf16x8*)(lds + PG8_SB(b, h) + boff + n * 2048 + k * 1024); } while (0)
; #define PG8_MMA(ai, bj, At, Bt) do { __builtin_amdgcn_s_setprio(1); _Pragma("unroll") for (int m = 0; m < 4; ++m) _Pragma("unroll") for (int n = 0; n < 2; ++n) _Pragma("unroll") for (int k = 0; k < 2; ++k) \
;         acc[ai][bj][m][n] = __builtin_amdgcn_mfma_f32_16x16x32_bf16(Bt[n][k], At[m][k], acc[ai][bj][m][n], 0, 0, 0); __builtin_amdgcn_s_setprio(0); } while (0)
; template <class Epi, class Sched, bool ALIGN_EPI = false, bool SP2 = false>
; __device__ __forceinline__ void gemm_phase(PG8_LAS unsigned char* lds, const Gemm g, const Sched& S, const Epi& E, int wv) {
;     ...
;             if constexpr (SP2) {
;             PG8_LDB(B0, 0, 0); PG8_LDB(B1, 0, 1); PG8_SCHED; PG8_LDA(At, 0, 0); PG8_STAGE(PG8_SA(1, 1), a1 + hstepA, voffA);
;             PG8_WAIT_V(8); PG8_WAIT_L(0); PG8_BAR; PG8_MMA(0, 0, At, B0); PG8_MMA(0, 1, At, B1); PG8_BAR; PG8_SCHED;
;             PG8_LDA(At, 0, 1); PG8_STAGE(PG8_SB(0, 0), b2, voffB); PG8_STAGE(PG8_SB(0, 1), b2 + hstepB, voffB); PG8_STAGE(PG8_SA(0, 0), a2, voffA);
;             PG8_WAIT_V(8); PG8_WAIT_L(0); PG8_BAR; PG8_MMA(1, 0, At, B0); PG8_MMA(1, 1, At, B1); PG8_BAR; PG8_SCHED;
;             PG8_LDB(B0, 1, 0); PG8_LDB(B1, 1, 1); PG8_SCHED; PG8_LDA(At, 1, 0); PG8_STAGE(PG8_SA(0, 1), a2 + hstepA, voffA);
;             PG8_WAIT_V(8); PG8_WAIT_L(0); PG8_BAR; PG8_MMA(0, 0, At, B0); PG8_MMA(0, 1, At, B1); PG8_BAR; PG8_SCHED;
;             PG8_LDA(At, 1, 1); PG8_STAGE(PG8_SB(1, 0), b3, voffB); PG8_STAGE(PG8_SB(1, 1), b3 + hstepB, voffB); PG8_STAGE(PG8_SA(1, 0), a3, voffA);
;             PG8_WAIT_V(8); PG8_WAIT_L(0); PG8_BAR; PG8_MMA(1, 0, At, B0); PG8_MMA(1, 1, At, B1); PG8_BAR; PG8_SCHED;
.LBB0_358:
	s_add_u32 s14, s12, 0xfffc0080
	s_addc_u32 s15, s13, -1
	s_add_i32 s74, 0, 0x10000
	s_cmp_eq_u32 s73, 12
	s_cselect_b32 s17, s11, s15
	s_cselect_b32 s16, s46, s14
	v_add_u32_e32 v0, s74, v149
	s_cselect_b32 s15, s1, s72
	s_cselect_b32 s14, s67, s69
	s_add_i32 s76, 0, 0x14000
	ds_read_b128 v[150:153], v0
	ds_read_b128 v[166:169], v0 offset:1024
	ds_read_b128 v[170:173], v0 offset:2048
	ds_read_b128 v[174:177], v0 offset:3072
	v_add_u32_e32 v0, s76, v149
	ds_read_b128 v[178:181], v0
	ds_read_b128 v[182:185], v0 offset:1024
	ds_read_b128 v[186:189], v0 offset:2048
	ds_read_b128 v[190:193], v0 offset:3072
	v_lshl_add_u64 v[154:155], s[12:13], 0, v[144:145]
	s_add_i32 m0, s31, 0xc000
	ds_read_b128 v[198:201], v164
	ds_read_b128 v[218:221], v164 offset:1024
	ds_read_b128 v[222:225], v164 offset:2048
	ds_read_b128 v[226:229], v164 offset:3072
	ds_read_b128 v[230:233], v164 offset:4096
	ds_read_b128 v[234:237], v164 offset:5120
	ds_read_b128 v[238:241], v164 offset:6144
	ds_read_b128 v[242:245], v164 offset:7168
	global_load_lds_dwordx4 v[154:155], off
	v_lshl_add_u64 v[154:155], s[12:13], 0, v[146:147]
	s_add_i32 m0, s31, 0xe000
	s_nop 0
	global_load_lds_dwordx4 v[154:155], off
	s_waitcnt vmcnt(8) lgkmcnt(0)
	s_barrier
	s_setprio 1
	v_mfma_f32_16x16x32_bf16 v[126:129], v[150:153], v[198:201], v[126:129]
	v_mfma_f32_16x16x32_bf16 v[122:125], v[170:173], v[198:201], v[122:125]
	v_mfma_f32_16x16x32_bf16 v[110:113], v[150:153], v[222:225], v[110:113]
	v_mfma_f32_16x16x32_bf16 v[106:109], v[170:173], v[222:225], v[106:109]
	v_mfma_f32_16x16x32_bf16 v[94:97], v[150:153], v[230:233], v[94:97]
	v_mfma_f32_16x16x32_bf16 v[90:93], v[170:173], v[230:233], v[90:93]
	v_mfma_f32_16x16x32_bf16 v[78:81], v[150:153], v[238:241], v[78:81]
	v_mfma_f32_16x16x32_bf16 v[74:77], v[170:173], v[238:241], v[74:77]
	v_mfma_f32_16x16x32_bf16 v[126:129], v[166:169], v[218:221], v[126:129]
	v_mfma_f32_16x16x32_bf16 v[122:125], v[174:177], v[218:221], v[122:125]
	v_mfma_f32_16x16x32_bf16 v[110:113], v[166:169], v[226:229], v[110:113]
	v_mfma_f32_16x16x32_bf16 v[106:109], v[174:177], v[226:229], v[106:109]
	v_mfma_f32_16x16x32_bf16 v[94:97], v[166:169], v[234:237], v[94:97]
	v_mfma_f32_16x16x32_bf16 v[90:93], v[174:177], v[234:237], v[90:93]
	v_mfma_f32_16x16x32_bf16 v[78:81], v[166:169], v[242:245], v[78:81]
	v_mfma_f32_16x16x32_bf16 v[74:77], v[174:177], v[242:245], v[74:77]
	v_mfma_f32_16x16x32_bf16 v[118:121], v[178:181], v[198:201], v[118:121]
	v_mfma_f32_16x16x32_bf16 v[114:117], v[186:189], v[198:201], v[114:117]
	v_mfma_f32_16x16x32_bf16 v[102:105], v[178:181], v[222:225], v[102:105]
	v_mfma_f32_16x16x32_bf16 v[98:101], v[186:189], v[222:225], v[98:101]
	v_mfma_f32_16x16x32_bf16 v[86:89], v[178:181], v[230:233], v[86:89]
	v_mfma_f32_16x16x32_bf16 v[82:85], v[186:189], v[230:233], v[82:85]
	v_mfma_f32_16x16x32_bf16 v[70:73], v[178:181], v[238:241], v[70:73]
	v_mfma_f32_16x16x32_bf16 v[66:69], v[186:189], v[238:241], v[66:69]
	v_mfma_f32_16x16x32_bf16 v[118:121], v[182:185], v[218:221], v[118:121]
	v_mfma_f32_16x16x32_bf16 v[114:117], v[190:193], v[218:221], v[114:117]
	v_mfma_f32_16x16x32_bf16 v[102:105], v[182:185], v[226:229], v[102:105]
	v_mfma_f32_16x16x32_bf16 v[98:101], v[190:193], v[226:229], v[98:101]
	v_mfma_f32_16x16x32_bf16 v[86:89], v[182:185], v[234:237], v[86:89]
	v_mfma_f32_16x16x32_bf16 v[82:85], v[190:193], v[234:237], v[82:85]
	v_mfma_f32_16x16x32_bf16 v[70:73], v[182:185], v[242:245], v[70:73]
	v_mfma_f32_16x16x32_bf16 v[66:69], v[190:193], v[242:245], v[66:69]
	s_setprio 0
	s_barrier
	s_add_i32 s74, s74, s25
	v_lshl_add_u64 v[154:155], s[14:15], 0, v[132:133]
	s_mov_b32 m0, s74
	ds_read_b128 v[198:201], v164 offset:16384
	ds_read_b128 v[218:221], v164 offset:17408
	ds_read_b128 v[222:225], v164 offset:18432
	ds_read_b128 v[226:229], v164 offset:19456
	ds_read_b128 v[230:233], v164 offset:20480
	ds_read_b128 v[234:237], v164 offset:21504
	ds_read_b128 v[238:241], v164 offset:22528
	ds_read_b128 v[242:245], v164 offset:23552
	global_load_lds_dwordx4 v[154:155], off
	s_add_i32 m0, s74, 0x2000
	s_add_u32 s74, s14, 0x40000
	v_lshl_add_u64 v[194:195], s[14:15], 0, v[136:137]
	s_addc_u32 s75, s15, 0
	s_add_i32 s76, s76, s25
	global_load_lds_dwordx4 v[194:195], off
	v_lshl_add_u64 v[196:197], s[74:75], 0, v[132:133]
	s_mov_b32 m0, s76
	v_lshl_add_u64 v[202:203], s[16:17], 0, v[134:135]
	global_load_lds_dwordx4 v[196:197], off
	v_lshl_add_u64 v[196:197], s[74:75], 0, v[136:137]
	s_add_i32 m0, s76, 0x2000
	s_nop 0
	global_load_lds_dwordx4 v[196:197], off
	v_lshl_add_u64 v[196:197], s[16:17], 0, v[130:131]
	s_mov_b32 m0, s31
	s_nop 0
	global_load_lds_dwordx4 v[196:197], off
	s_mov_b32 m0, s33
	s_nop 0
	global_load_lds_dwordx4 v[202:203], off
	s_waitcnt vmcnt(8) lgkmcnt(0)
	s_barrier
; #define PG8_STAGE(bufoff, gbase, voff) do { _Pragma("unroll") for (int _i = 0; _i < 2; ++_i) \
;         __builtin_amdgcn_global_load_lds((const unsigned*)((const char*)(gbase) + (voff)[_i]), (PG8_LAS unsigned*)(lds + (bufoff) + ldsw + _i * 8192), 16, 0, 0); } while (0)
; #define PG8_LDA(dst, b, h) do { _Pragma("unroll") for (int m = 0; m < 4; ++m) _Pragma("unroll") for (int k = 0; k < 2; ++k) dst[m][k] = *(const PG8_LAS bf16x8*)(lds + PG8_SA(b, h) + aoff + m * 2048 + k * 1024); } while (0)
; #define PG8_LDB(dst, b, h) do { _Pragma("unroll") for (int n = 0; n < 2; ++n) _Pragma("unroll") for (int k = 0; k < 2; ++k) dst[n][k] = *(const PG8_LAS bf16x8*)(lds + PG8_SB(b, h) + boff + n * 2048 + k * 1024); } while (0)
; #define PG8_MMA(ai, bj, At, Bt) do { __builtin_amdgcn_s_setprio(1); _Pragma("unroll") for (int m = 0; m < 4; ++m) _Pragma("unroll") for (int n = 0; n < 2; ++n) _Pragma("unroll") for (int k = 0; k < 2; ++k) \
;         acc[ai][bj][m][n] = __builtin_amdgcn_mfma_f32_16x16x32_bf16(Bt[n][k], At[m][k], acc[ai][bj][m][n], 0, 0, 0); __builtin_amdgcn_s_setprio(0); } while (0)
; template <class Epi, class Sched, bool ALIGN_EPI = false, bool SP2 = false>
; __device__ __forceinline__ void gemm_phase(PG8_LAS unsigned char* lds, const Gemm g, const Sched& S, const Epi& E, int wv) {
;     ...
;             if constexpr (SP2) {
;             PG8_LDB(B0, 0, 0); PG8_LDB(B1, 0, 1); PG8_SCHED; PG8_LDA(At, 0, 0); PG8_STAGE(PG8_SA(1, 1), a1 + hstepA, voffA);
;             PG8_WAIT_V(8); PG8_WAIT_L(0); PG8_BAR; PG8_MMA(0, 0, At, B0); PG8_MMA(0, 1, At, B1); PG8_BAR; PG8_SCHED;
;             PG8_LDA(At, 0, 1); PG8_STAGE(PG8_SB(0, 0), b2, voffB); PG8_STAGE(PG8_SB(0, 1), b2 + hstepB, voffB); PG8_STAGE(PG8_SA(0, 0), a2, voffA);
;             PG8_WAIT_V(8); PG8_WAIT_L(0); PG8_BAR; PG8_MMA(1, 0, At, B0); PG8_MMA(1, 1, At, B1); PG8_BAR; PG8_SCHED;
;             PG8_LDB(B0, 1, 0); PG8_LDB(B1, 1, 1); PG8_SCHED; PG8_LDA(At, 1, 0); PG8_STAGE(PG8_SA(0, 1), a2 + hstepA, voffA);
;             PG8_WAIT_V(8); PG8_WAIT_L(0); PG8_BAR; PG8_MMA(0, 0, At, B0); PG8_MMA(0, 1, At, B1); PG8_BAR; PG8_SCHED;
;             PG8_LDA(At, 1, 1); PG8_STAGE(PG8_SB(1, 0), b3, voffB); PG8_STAGE(PG8_SB(1, 1), b3 + hstepB, voffB); PG8_STAGE(PG8_SA(1, 0), a3, voffA);
;             PG8_WAIT_V(8); PG8_WAIT_L(0); PG8_BAR; PG8_MMA(1, 0, At, B0); PG8_MMA(1, 1, At, B1); PG8_BAR; PG8_SCHED;
	s_setprio 1
	v_mfma_f32_16x16x32_bf16 v[62:65], v[150:153], v[198:201], v[62:65]
	v_mfma_f32_16x16x32_bf16 v[58:61], v[170:173], v[198:201], v[58:61]
	v_mfma_f32_16x16x32_bf16 v[46:49], v[150:153], v[222:225], v[46:49]
	v_mfma_f32_16x16x32_bf16 v[42:45], v[170:173], v[222:225], v[42:45]
	v_mfma_f32_16x16x32_bf16 v[30:33], v[150:153], v[230:233], v[30:33]
	v_mfma_f32_16x16x32_bf16 v[26:29], v[170:173], v[230:233], v[26:29]
	v_mfma_f32_16x16x32_bf16 v[14:17], v[150:153], v[238:241], v[14:17]
	v_mfma_f32_16x16x32_bf16 v[10:13], v[170:173], v[238:241], v[10:13]
	v_mfma_f32_16x16x32_bf16 v[62:65], v[166:169], v[218:221], v[62:65]
	v_mfma_f32_16x16x32_bf16 v[58:61], v[174:177], v[218:221], v[58:61]
	v_mfma_f32_16x16x32_bf16 v[46:49], v[166:169], v[226:229], v[46:49]
	v_mfma_f32_16x16x32_bf16 v[42:45], v[174:177], v[226:229], v[42:45]
	v_mfma_f32_16x16x32_bf16 v[30:33], v[166:169], v[234:237], v[30:33]
	v_mfma_f32_16x16x32_bf16 v[26:29], v[174:177], v[234:237], v[26:29]
	v_mfma_f32_16x16x32_bf16 v[14:17], v[166:169], v[242:245], v[14:17]
	v_mfma_f32_16x16x32_bf16 v[10:13], v[174:177], v[242:245], v[10:13]
	v_mfma_f32_16x16x32_bf16 v[54:57], v[178:181], v[198:201], v[54:57]
	v_mfma_f32_16x16x32_bf16 v[50:53], v[186:189], v[198:201], v[50:53]
	v_mfma_f32_16x16x32_bf16 v[38:41], v[178:181], v[222:225], v[38:41]
	v_mfma_f32_16x16x32_bf16 v[34:37], v[186:189], v[222:225], v[34:37]
	v_mfma_f32_16x16x32_bf16 v[22:25], v[178:181], v[230:233], v[22:25]
	v_mfma_f32_16x16x32_bf16 v[18:21], v[186:189], v[230:233], v[18:21]
	v_mfma_f32_16x16x32_bf16 v[6:9], v[178:181], v[238:241], v[6:9]
	v_mfma_f32_16x16x32_bf16 v[2:5], v[186:189], v[238:241], v[2:5]
	v_mfma_f32_16x16x32_bf16 v[54:57], v[182:185], v[218:221], v[54:57]
	v_mfma_f32_16x16x32_bf16 v[50:53], v[190:193], v[218:221], v[50:53]
	v_mfma_f32_16x16x32_bf16 v[38:41], v[182:185], v[226:229], v[38:41]
	v_mfma_f32_16x16x32_bf16 v[34:37], v[190:193], v[226:229], v[34:37]
	v_mfma_f32_16x16x32_bf16 v[22:25], v[182:185], v[234:237], v[22:25]
	v_mfma_f32_16x16x32_bf16 v[18:21], v[190:193], v[234:237], v[18:21]
	v_mfma_f32_16x16x32_bf16 v[6:9], v[182:185], v[242:245], v[6:9]
	v_mfma_f32_16x16x32_bf16 v[2:5], v[190:193], v[242:245], v[2:5]
	s_setprio 0
	s_barrier
	s_add_i32 s74, 0, 0x18000
	v_add_u32_e32 v0, s74, v149
	s_add_i32 s75, 0, 0x1c000
	ds_read_b128 v[150:153], v0
	ds_read_b128 v[166:169], v0 offset:1024
	ds_read_b128 v[170:173], v0 offset:2048
	ds_read_b128 v[174:177], v0 offset:3072
	v_add_u32_e32 v0, s75, v149
	ds_read_b128 v[178:181], v0
	ds_read_b128 v[182:185], v0 offset:1024
	ds_read_b128 v[186:189], v0 offset:2048
	ds_read_b128 v[190:193], v0 offset:3072
	s_add_u32 s16, s16, 0x40000
	s_addc_u32 s17, s17, 0
	s_mov_b32 m0, s38
	v_lshl_add_u64 v[204:205], s[16:17], 0, v[130:131]
	ds_read_b128 v[198:201], v164 offset:32768
	ds_read_b128 v[218:221], v164 offset:33792
	ds_read_b128 v[222:225], v164 offset:34816
	ds_read_b128 v[226:229], v164 offset:35840
	ds_read_b128 v[230:233], v164 offset:36864
	ds_read_b128 v[234:237], v164 offset:37888
	ds_read_b128 v[238:241], v164 offset:38912
	ds_read_b128 v[242:245], v164 offset:39936
	global_load_lds_dwordx4 v[204:205], off
	v_lshl_add_u64 v[204:205], s[16:17], 0, v[134:135]
	s_mov_b32 m0, s39
	s_nop 0
	global_load_lds_dwordx4 v[204:205], off
	s_waitcnt vmcnt(8) lgkmcnt(0)
	s_barrier
	s_setprio 1
	v_mfma_f32_16x16x32_bf16 v[126:129], v[150:153], v[198:201], v[126:129]
	v_mfma_f32_16x16x32_bf16 v[122:125], v[170:173], v[198:201], v[122:125]
	v_mfma_f32_16x16x32_bf16 v[110:113], v[150:153], v[222:225], v[110:113]
	v_mfma_f32_16x16x32_bf16 v[106:109], v[170:173], v[222:225], v[106:109]
	v_mfma_f32_16x16x32_bf16 v[94:97], v[150:153], v[230:233], v[94:97]
	v_mfma_f32_16x16x32_bf16 v[90:93], v[170:173], v[230:233], v[90:93]
	v_mfma_f32_16x16x32_bf16 v[78:81], v[150:153], v[238:241], v[78:81]
	v_mfma_f32_16x16x32_bf16 v[74:77], v[170:173], v[238:241], v[74:77]
	v_mfma_f32_16x16x32_bf16 v[126:129], v[166:169], v[218:221], v[126:129]
	v_mfma_f32_16x16x32_bf16 v[122:125], v[174:177], v[218:221], v[122:125]
	v_mfma_f32_16x16x32_bf16 v[110:113], v[166:169], v[226:229], v[110:113]
	v_mfma_f32_16x16x32_bf16 v[106:109], v[174:177], v[226:229], v[106:109]
	v_mfma_f32_16x16x32_bf16 v[94:97], v[166:169], v[234:237], v[94:97]
	v_mfma_f32_16x16x32_bf16 v[90:93], v[174:177], v[234:237], v[90:93]
	v_mfma_f32_16x16x32_bf16 v[78:81], v[166:169], v[242:245], v[78:81]
	v_mfma_f32_16x16x32_bf16 v[74:77], v[174:177], v[242:245], v[74:77]
	v_mfma_f32_16x16x32_bf16 v[118:121], v[178:181], v[198:201], v[118:121]
	v_mfma_f32_16x16x32_bf16 v[114:117], v[186:189], v[198:201], v[114:117]
	v_mfma_f32_16x16x32_bf16 v[102:105], v[178:181], v[222:225], v[102:105]
	v_mfma_f32_16x16x32_bf16 v[98:101], v[186:189], v[222:225], v[98:101]
	v_mfma_f32_16x16x32_bf16 v[86:89], v[178:181], v[230:233], v[86:89]
	v_mfma_f32_16x16x32_bf16 v[82:85], v[186:189], v[230:233], v[82:85]
	v_mfma_f32_16x16x32_bf16 v[70:73], v[178:181], v[238:241], v[70:73]
	v_mfma_f32_16x16x32_bf16 v[66:69], v[186:189], v[238:241], v[66:69]
	v_mfma_f32_16x16x32_bf16 v[118:121], v[182:185], v[218:221], v[118:121]
	v_mfma_f32_16x16x32_bf16 v[114:117], v[190:193], v[218:221], v[114:117]
	v_mfma_f32_16x16x32_bf16 v[102:105], v[182:185], v[226:229], v[102:105]
	v_mfma_f32_16x16x32_bf16 v[98:101], v[190:193], v[226:229], v[98:101]
	v_mfma_f32_16x16x32_bf16 v[86:89], v[182:185], v[234:237], v[86:89]
	v_mfma_f32_16x16x32_bf16 v[82:85], v[190:193], v[234:237], v[82:85]
	v_mfma_f32_16x16x32_bf16 v[70:73], v[182:185], v[242:245], v[70:73]
	v_mfma_f32_16x16x32_bf16 v[66:69], v[190:193], v[242:245], v[66:69]
	s_setprio 0
	s_barrier
; #define PG8_STAGE(bufoff, gbase, voff) do { _Pragma("unroll") for (int _i = 0; _i < 2; ++_i) \
;         __builtin_amdgcn_global_load_lds((const unsigned*)((const char*)(gbase) + (voff)[_i]), (PG8_LAS unsigned*)(lds + (bufoff) + ldsw + _i * 8192), 16, 0, 0); } while (0)
; #define PG8_LDA(dst, b, h) do { _Pragma("unroll") for (int m = 0; m < 4; ++m) _Pragma("unroll") for (int k = 0; k < 2; ++k) dst[m][k] = *(const PG8_LAS bf16x8*)(lds + PG8_SA(b, h) + aoff + m * 2048 + k * 1024); } while (0)
; #define PG8_LDB(dst, b, h) do { _Pragma("unroll") for (int n = 0; n < 2; ++n) _Pragma("unroll") for (int k = 0; k < 2; ++k) dst[n][k] = *(const PG8_LAS bf16x8*)(lds + PG8_SB(b, h) + boff + n * 2048 + k * 1024); } while (0)
; #define PG8_WAIT_V(n) asm volatile("s_waitcnt vmcnt(" #n ")" ::: "memory")
; #define PG8_WAIT_L(n) asm volatile("s_waitcnt lgkmcnt(" #n ")" ::: "memory")
; #define PG8_BAR __builtin_amdgcn_s_barrier()
; #define PG8_SCHED __builtin_amdgcn_sched_barrier(0)
; template <class Epi, class Sched, bool ALIGN_EPI = false, bool SP2 = false>
; __device__ __forceinline__ void gemm_phase(PG8_LAS unsigned char* lds, const Gemm g, const Sched& S, const Epi& E, int wv) {
;     ...
;         for (int t = 0; t < nt; t += 2) {
;     ...
;             if constexpr (SP2) {
;             PG8_LDB(B0, 0, 0); PG8_LDB(B1, 0, 1); PG8_SCHED; PG8_LDA(At, 0, 0); PG8_STAGE(PG8_SA(1, 1), a1 + hstepA, voffA);
;             PG8_WAIT_V(8); PG8_WAIT_L(0); PG8_BAR; PG8_MMA(0, 0, At, B0); PG8_MMA(0, 1, At, B1); PG8_BAR; PG8_SCHED;
;             PG8_LDA(At, 0, 1); PG8_STAGE(PG8_SB(0, 0), b2, voffB); PG8_STAGE(PG8_SB(0, 1), b2 + hstepB, voffB); PG8_STAGE(PG8_SA(0, 0), a2, voffA);
;             PG8_WAIT_V(8); PG8_WAIT_L(0); PG8_BAR; PG8_MMA(1, 0, At, B0); PG8_MMA(1, 1, At, B1); PG8_BAR; PG8_SCHED;
;             PG8_LDB(B0, 1, 0); PG8_LDB(B1, 1, 1); PG8_SCHED; PG8_LDA(At, 1, 0); PG8_STAGE(PG8_SA(0, 1), a2 + hstepA, voffA);
;             PG8_WAIT_V(8); PG8_WAIT_L(0); PG8_BAR; PG8_MMA(0, 0, At, B0); PG8_MMA(0, 1, At, B1); PG8_BAR; PG8_SCHED;
;             PG8_LDA(At, 1, 1); PG8_STAGE(PG8_SB(1, 0), b3, voffB); PG8_STAGE(PG8_SB(1, 1), b3 + hstepB, voffB); PG8_STAGE(PG8_SA(1, 0), a3, voffA);
;             PG8_WAIT_V(8); PG8_WAIT_L(0); PG8_BAR; PG8_MMA(1, 0, At, B0); PG8_MMA(1, 1, At, B1); PG8_BAR; PG8_SCHED;
;     ...
;         if constexpr (ALIGN_EPI) { if (wr == 0) PG8_BAR; }
	s_add_i32 s16, s74, s25
	v_lshl_add_u64 v[154:155], v[154:155], 0, s[20:21]
	s_mov_b32 m0, s16
	ds_read_b128 v[198:201], v164 offset:49152
	ds_read_b128 v[218:221], v164 offset:50176
	ds_read_b128 v[222:225], v164 offset:51200
	ds_read_b128 v[226:229], v164 offset:52224
	ds_read_b128 v[230:233], v164 offset:53248
	ds_read_b128 v[234:237], v164 offset:54272
	ds_read_b128 v[238:241], v164 offset:55296
	ds_read_b128 v[242:245], v164 offset:56320
	global_load_lds_dwordx4 v[154:155], off
	s_add_i32 m0, s16, 0x2000
	s_add_u32 s14, s14, 0x40080
	v_lshl_add_u64 v[154:155], v[194:195], 0, s[20:21]
	s_addc_u32 s15, s15, 0
	s_add_i32 s16, s75, s25
	global_load_lds_dwordx4 v[154:155], off
	v_lshl_add_u64 v[154:155], s[14:15], 0, v[132:133]
	s_mov_b32 m0, s16
	s_nop 0
	global_load_lds_dwordx4 v[154:155], off
	v_lshl_add_u64 v[154:155], s[14:15], 0, v[136:137]
	s_add_i32 m0, s16, 0x2000
	s_nop 0
	global_load_lds_dwordx4 v[154:155], off
	v_lshl_add_u64 v[154:155], v[196:197], 0, s[20:21]
	s_mov_b32 m0, s41
	s_nop 0
	global_load_lds_dwordx4 v[154:155], off
	v_lshl_add_u64 v[154:155], v[202:203], 0, s[20:21]
	s_mov_b32 m0, s42
	s_nop 0
	global_load_lds_dwordx4 v[154:155], off
	s_waitcnt vmcnt(8) lgkmcnt(0)
	s_barrier
	s_setprio 1
	v_mfma_f32_16x16x32_bf16 v[62:65], v[150:153], v[198:201], v[62:65]
	v_mfma_f32_16x16x32_bf16 v[58:61], v[170:173], v[198:201], v[58:61]
	v_mfma_f32_16x16x32_bf16 v[46:49], v[150:153], v[222:225], v[46:49]
	v_mfma_f32_16x16x32_bf16 v[42:45], v[170:173], v[222:225], v[42:45]
	v_mfma_f32_16x16x32_bf16 v[30:33], v[150:153], v[230:233], v[30:33]
	v_mfma_f32_16x16x32_bf16 v[26:29], v[170:173], v[230:233], v[26:29]
	v_mfma_f32_16x16x32_bf16 v[14:17], v[150:153], v[238:241], v[14:17]
	v_mfma_f32_16x16x32_bf16 v[10:13], v[170:173], v[238:241], v[10:13]
	v_mfma_f32_16x16x32_bf16 v[62:65], v[166:169], v[218:221], v[62:65]
	v_mfma_f32_16x16x32_bf16 v[58:61], v[174:177], v[218:221], v[58:61]
	v_mfma_f32_16x16x32_bf16 v[46:49], v[166:169], v[226:229], v[46:49]
	v_mfma_f32_16x16x32_bf16 v[42:45], v[174:177], v[226:229], v[42:45]
	v_mfma_f32_16x16x32_bf16 v[30:33], v[166:169], v[234:237], v[30:33]
	v_mfma_f32_16x16x32_bf16 v[26:29], v[174:177], v[234:237], v[26:29]
	v_mfma_f32_16x16x32_bf16 v[14:17], v[166:169], v[242:245], v[14:17]
	v_mfma_f32_16x16x32_bf16 v[10:13], v[174:177], v[242:245], v[10:13]
	v_mfma_f32_16x16x32_bf16 v[54:57], v[178:181], v[198:201], v[54:57]
	v_mfma_f32_16x16x32_bf16 v[50:53], v[186:189], v[198:201], v[50:53]
	v_mfma_f32_16x16x32_bf16 v[38:41], v[178:181], v[222:225], v[38:41]
	v_mfma_f32_16x16x32_bf16 v[34:37], v[186:189], v[222:225], v[34:37]
	v_mfma_f32_16x16x32_bf16 v[22:25], v[178:181], v[230:233], v[22:25]
	v_mfma_f32_16x16x32_bf16 v[18:21], v[186:189], v[230:233], v[18:21]
	v_mfma_f32_16x16x32_bf16 v[6:9], v[178:181], v[238:241], v[6:9]
	v_mfma_f32_16x16x32_bf16 v[2:5], v[186:189], v[238:241], v[2:5]
	v_mfma_f32_16x16x32_bf16 v[54:57], v[182:185], v[218:221], v[54:57]
	v_mfma_f32_16x16x32_bf16 v[50:53], v[190:193], v[218:221], v[50:53]
	v_mfma_f32_16x16x32_bf16 v[38:41], v[182:185], v[226:229], v[38:41]
	v_mfma_f32_16x16x32_bf16 v[34:37], v[190:193], v[226:229], v[34:37]
	v_mfma_f32_16x16x32_bf16 v[22:25], v[182:185], v[234:237], v[22:25]
	v_mfma_f32_16x16x32_bf16 v[18:21], v[190:193], v[234:237], v[18:21]
	v_mfma_f32_16x16x32_bf16 v[6:9], v[182:185], v[242:245], v[6:9]
	v_mfma_f32_16x16x32_bf16 v[2:5], v[190:193], v[242:245], v[2:5]
	s_setprio 0
	s_barrier
	s_add_i32 s73, s73, 2
	s_add_u32 s12, s12, 0x100
	s_addc_u32 s13, s13, 0
	s_add_u32 s69, s69, 0x100
	s_addc_u32 s72, s72, 0
	s_cmp_gt_u32 s73, 13
	s_cbranch_scc0 .LBB0_358
	s_and_b64 vcc, exec, s[8:9]
	s_cbranch_vccz .LBB0_361
	s_barrier
